# MLA (tiles by global_load_lds): waves 4-7 meet the barrier behind their 3rd PV MFMA
# baseline (speedup 1.0000x reference)
; __device__ __forceinline__ void finishSM9(f32x16& p0, f32x16& p1, float alpha, float& l_reg, v8i32& p8) {
; #pragma unroll
;   for (int r = 0; r < 16; ++r) { p0[r] = __builtin_amdgcn_exp2f(p0[r]); p1[r] = __builtin_amdgcn_exp2f(p1[r]); }
;   float ps = 0;
; #pragma unroll
;   for (int r = 0; r < 16; ++r) ps += p0[r];
; #pragma unroll
;   for (int r = 0; r < 16; ++r) ps += p1[r];
;   { auto rr = __builtin_amdgcn_permlane32_swap(__float_as_uint(ps), __float_as_uint(ps), false, false);
;     ps = __uint_as_float(rr[0]) + __uint_as_float(rr[1]); }
;   l_reg = l_reg * alpha + ps;
; #pragma unroll
;   for (int g = 0; g < 4; ++g) {
;     int w = __builtin_amdgcn_cvt_pk_fp8_f32(p0[4 * g], p0[4 * g + 1], 0, false); p8[g] = __builtin_amdgcn_cvt_pk_fp8_f32(p0[4 * g + 2], p0[4 * g + 3], w, true);
;     int u = __builtin_amdgcn_cvt_pk_fp8_f32(p1[4 * g], p1[4 * g + 1], 0, false); p8[4 + g] = __builtin_amdgcn_cvt_pk_fp8_f32(p1[4 * g + 2], p1[4 * g + 3], u, true); }
; }
; __device__ __forceinline__ void pv8(f32x16* o, const char* Vt, const v8i32 p8, int r32, int hi) {
;   const int sw = (r32 >> 2) & 3, a0 = r32 * 64 + (((hi * 2) ^ sw) << 4), a1 = r32 * 64 + (((hi * 2 + 1) ^ sw) << 4);
; #pragma unroll
;   for (int d0 = 0; d0 < 4; ++d0) {
;     const v8i32 vf = cat8(*reinterpret_cast<const v4i32*>(Vt + d0 * 2048 + a0), *reinterpret_cast<const v4i32*>(Vt + d0 * 2048 + a1));
;     o[d0] = __builtin_amdgcn_mfma_scale_f32_32x32x64_f8f6f4(p8, vf, o[d0], 0, 0, 0, 127, 0, 127); }
; }
; __device__ __forceinline__ void qkt9(f32x16& p0, f32x16& p1, const char* Kn, const char* Kr, const v8i32* qf, const float init, int r32, int hi) {
; #pragma unroll
;   for (int r = 0; r < 16; ++r) { p0[r] = init; p1[r] = init; }
; #pragma unroll
;   for (int s = 0; s < 2; ++s) { const int c0 = s * 4 + hi * 2;
;     const v8i32 a0 = cat8(*reinterpret_cast<const v4i32*>(Kn + KN8SW(r32, c0)), *reinterpret_cast<const v4i32*>(Kn + KN8SW(r32, c0 + 1)));
;     const v8i32 a1 = cat8(*reinterpret_cast<const v4i32*>(Kn + 4096 + KN8SW(r32, c0)), *reinterpret_cast<const v4i32*>(Kn + 4096 + KN8SW(r32, c0 + 1)));
;     p0 = __builtin_amdgcn_mfma_scale_f32_32x32x64_f8f6f4(a0, qf[s], p0, 0, 0, 0, 127, 0, 124);
;     p1 = __builtin_amdgcn_mfma_scale_f32_32x32x64_f8f6f4(a1, qf[s], p1, 0, 0, 0, 127, 0, 124); }
;   { const int c0 = hi * 2;
.Lmla_stag_loop:
	ds_read_b128 v[114:117], v215 offset:24576
	ds_read_b128 v[118:121], v216 offset:24576
	ds_read_b128 v[222:225], v215 offset:28672
	ds_read_b128 v[226:229], v216 offset:28672
	v_exp_f32_e32 v0, v82
	v_exp_f32_e32 v177, v83
	v_exp_f32_e32 v179, v84
	v_exp_f32_e32 v254, v85
	v_add_f32_e32 v219, v0, v177
	v_cvt_pk_fp8_f32 v246, v0, v177
	v_add_f32_e32 v219, v179, v219
	v_add_f32_e32 v219, v254, v219
	v_cvt_pk_fp8_f32 v246, v179, v254 op_sel:[0,0,1]
	s_waitcnt lgkmcnt(2)
	v_mfma_scale_f32_32x32x64_f8f6f4 v[114:129], v[114:121], v[146:153], v[230:245], v194, v193 op_sel_hi:[0,0,0]
	v_exp_f32_e32 v0, v86
	v_exp_f32_e32 v177, v87
	v_exp_f32_e32 v179, v88
	v_exp_f32_e32 v254, v89
	v_add_f32_e32 v219, v0, v219
	v_add_f32_e32 v219, v177, v219
	v_cvt_pk_fp8_f32 v247, v0, v177
	v_add_f32_e32 v219, v179, v219
	v_add_f32_e32 v219, v254, v219
	v_cvt_pk_fp8_f32 v247, v179, v254 op_sel:[0,0,1]
	ds_read_b128 v[82:85], v213 offset:24576
	ds_read_b128 v[86:89], v214 offset:24576
	s_waitcnt lgkmcnt(2)
	v_mfma_scale_f32_32x32x64_f8f6f4 v[98:113], v[222:229], v[146:153], v[230:245], v194, v193 op_sel_hi:[0,0,0]
	ds_read_b128 v[222:225], v213 offset:28672
	ds_read_b128 v[226:229], v214 offset:28672
	v_exp_f32_e32 v0, v90
	v_exp_f32_e32 v177, v91
	v_exp_f32_e32 v179, v92
	v_exp_f32_e32 v254, v93
	v_add_f32_e32 v219, v0, v219
	v_add_f32_e32 v219, v177, v219
	v_cvt_pk_fp8_f32 v248, v0, v177
	v_add_f32_e32 v219, v179, v219
	v_add_f32_e32 v219, v254, v219
	v_cvt_pk_fp8_f32 v248, v179, v254 op_sel:[0,0,1]
	v_exp_f32_e32 v0, v94
	v_exp_f32_e32 v177, v95
	v_exp_f32_e32 v179, v96
	v_exp_f32_e32 v254, v97
	v_add_f32_e32 v219, v0, v219
	v_add_f32_e32 v219, v177, v219
	v_cvt_pk_fp8_f32 v249, v0, v177
	v_add_f32_e32 v219, v179, v219
	v_add_f32_e32 v219, v254, v219
	v_cvt_pk_fp8_f32 v249, v179, v254 op_sel:[0,0,1]
	ds_read_b128 v[90:93], v185 offset:36864
	ds_read_b128 v[94:97], v186 offset:36864
	s_waitcnt lgkmcnt(4)
	v_mfma_scale_f32_32x32x64_f8f6f4 v[114:129], v[82:89], v[138:145], v[114:129], v194, v193 op_sel_hi:[0,0,0]
	v_exp_f32_e32 v0, v66
	v_exp_f32_e32 v177, v67
	v_exp_f32_e32 v179, v68
	v_exp_f32_e32 v254, v69
	v_add_f32_e32 v219, v0, v219
	v_add_f32_e32 v219, v177, v219
	v_cvt_pk_fp8_f32 v250, v0, v177
	v_add_f32_e32 v219, v179, v219
	v_add_f32_e32 v219, v254, v219
	v_cvt_pk_fp8_f32 v250, v179, v254 op_sel:[0,0,1]
	s_waitcnt lgkmcnt(2)
	v_mfma_scale_f32_32x32x64_f8f6f4 v[98:113], v[222:229], v[138:145], v[98:113], v194, v193 op_sel_hi:[0,0,0]
	ds_read_b128 v[222:225], v185 offset:38912
	ds_read_b128 v[226:229], v186 offset:38912
	v_exp_f32_e32 v0, v70
	v_exp_f32_e32 v177, v71
	v_exp_f32_e32 v179, v72
	v_exp_f32_e32 v254, v73
	v_add_f32_e32 v219, v0, v219
	v_add_f32_e32 v219, v177, v219
	v_cvt_pk_fp8_f32 v251, v0, v177
	v_add_f32_e32 v219, v179, v219
	v_add_f32_e32 v219, v254, v219
	v_cvt_pk_fp8_f32 v251, v179, v254 op_sel:[0,0,1]
	v_exp_f32_e32 v0, v74
	v_exp_f32_e32 v177, v75
	v_exp_f32_e32 v179, v76
	v_exp_f32_e32 v254, v77
	v_add_f32_e32 v219, v0, v219
	v_add_f32_e32 v219, v177, v219
	v_cvt_pk_fp8_f32 v252, v0, v177
	v_add_f32_e32 v219, v179, v219
	v_add_f32_e32 v219, v254, v219
	v_cvt_pk_fp8_f32 v252, v179, v254 op_sel:[0,0,1]
	s_waitcnt lgkmcnt(2)
	v_mfma_scale_f32_32x32x64_f8f6f4 v[114:129], v[90:97], v[130:137], v[114:129], v194, v193 op_sel_hi:[0,0,0]
	v_exp_f32_e32 v0, v78
	v_exp_f32_e32 v177, v79
	v_exp_f32_e32 v179, v80
	v_exp_f32_e32 v254, v81
	v_add_f32_e32 v219, v0, v219
	v_add_f32_e32 v219, v177, v219
	v_cvt_pk_fp8_f32 v253, v0, v177
	v_add_f32_e32 v219, v179, v219
	v_add_f32_e32 v219, v254, v219
	v_cvt_pk_fp8_f32 v253, v179, v254 op_sel:[0,0,1]
	ds_read_b128 v[90:93], v185 offset:0
	ds_read_b128 v[94:97], v186 offset:0
	ds_read_b128 v[82:85], v185 offset:2048
	ds_read_b128 v[86:89], v186 offset:2048
	ds_read_b128 v[74:77], v185 offset:4096
	ds_read_b128 v[78:81], v186 offset:4096
	ds_read_b128 v[66:69], v185 offset:6144
	ds_read_b128 v[70:73], v186 offset:6144
	s_waitcnt lgkmcnt(8)
	v_mfma_scale_f32_32x32x64_f8f6f4 v[98:113], v[222:229], v[130:137], v[98:113], v194, v193 op_sel_hi:[0,0,0]
	v_mov_b32_e32 v0, v219
	s_nop 1
	v_permlane32_swap_b32_e32 v219, v0
	v_add_f32_e32 v219, v219, v0
	v_fma_f32 v209, v209, v218, v219
	v_max_f32_e32 v177, v114, v115
	v_max3_f32 v177, v177, v116, v117
	v_max3_f32 v177, v177, v118, v119
	v_max3_f32 v177, v177, v120, v121
	v_max3_f32 v177, v177, v122, v123
	v_max3_f32 v177, v177, v124, v125
	v_max3_f32 v177, v177, v126, v127
	v_max3_f32 v177, v177, v128, v129
	s_waitcnt lgkmcnt(6)
	v_mfma_scale_f32_32x32x64_f8f6f4 v[50:65], v[246:253], v[90:97], v[50:65], v194, v194 op_sel_hi:[0,0,0]
	s_waitcnt lgkmcnt(4)
	v_mfma_scale_f32_32x32x64_f8f6f4 v[34:49], v[246:253], v[82:89], v[34:49], v194, v194 op_sel_hi:[0,0,0]
	s_waitcnt lgkmcnt(2)
	v_mfma_scale_f32_32x32x64_f8f6f4 v[18:33], v[246:253], v[74:81], v[18:33], v194, v194 op_sel_hi:[0,0,0]
	s_waitcnt vmcnt(0)
	s_waitcnt lgkmcnt(0)
	s_barrier
	s_waitcnt lgkmcnt(0)
	v_mfma_scale_f32_32x32x64_f8f6f4 v[2:17], v[246:253], v[66:73], v[2:17], v194, v194 op_sel_hi:[0,0,0]
	s_add_i32 m0, s98, 0x0
	s_nop 0
	global_load_lds_dwordx4 v176, s[18:19]
	s_add_i32 m0, s98, 0x4000
	s_nop 0
	global_load_lds_dwordx4 v178, s[16:17]
	v_add_u32_e32 v176, 0x2000, v176
	v_add_u32_e32 v178, 0x20000, v178
	v_max_f32_e32 v0, v98, v99
	v_max3_f32 v0, v0, v100, v101
	v_max3_f32 v0, v0, v102, v103
	v_max3_f32 v0, v0, v104, v105
	v_max3_f32 v0, v0, v106, v107
	v_max3_f32 v0, v0, v108, v109
	v_max3_f32 v0, v0, v110, v111
	v_max3_f32 v0, v0, v112, v113
	v_max_f32_e32 v177, v177, v0
	v_mov_b32_e32 v0, v177
	v_mov_b32_e32 v221, 1.0
	s_nop 0
	v_permlane32_swap_b32_e32 v177, v0
	v_max_f32_e32 v177, v177, v0
	v_cmp_ge_f32_e32 vcc, s90, v177
	s_cmp_eq_u64 vcc, exec
	s_cbranch_scc0 .Lmla_s0_newmax
; __device__ __forceinline__ void finishSM9(f32x16& p0, f32x16& p1, float alpha, float& l_reg, v8i32& p8) {
; #pragma unroll
;   for (int r = 0; r < 16; ++r) { p0[r] = __builtin_amdgcn_exp2f(p0[r]); p1[r] = __builtin_amdgcn_exp2f(p1[r]); }
;   float ps = 0;
; #pragma unroll
;   for (int r = 0; r < 16; ++r) ps += p0[r];
; #pragma unroll
;   for (int r = 0; r < 16; ++r) ps += p1[r];
;   { auto rr = __builtin_amdgcn_permlane32_swap(__float_as_uint(ps), __float_as_uint(ps), false, false);
;     ps = __uint_as_float(rr[0]) + __uint_as_float(rr[1]); }
;   l_reg = l_reg * alpha + ps;
; #pragma unroll
;   for (int g = 0; g < 4; ++g) {
;     int w = __builtin_amdgcn_cvt_pk_fp8_f32(p0[4 * g], p0[4 * g + 1], 0, false); p8[g] = __builtin_amdgcn_cvt_pk_fp8_f32(p0[4 * g + 2], p0[4 * g + 3], w, true);
;     int u = __builtin_amdgcn_cvt_pk_fp8_f32(p1[4 * g], p1[4 * g + 1], 0, false); p8[4 + g] = __builtin_amdgcn_cvt_pk_fp8_f32(p1[4 * g + 2], p1[4 * g + 3], u, true); }
; }
; __device__ __forceinline__ void pv8(f32x16* o, const char* Vt, const v8i32 p8, int r32, int hi) {
;   const int sw = (r32 >> 2) & 3, a0 = r32 * 64 + (((hi * 2) ^ sw) << 4), a1 = r32 * 64 + (((hi * 2 + 1) ^ sw) << 4);
; #pragma unroll
;   for (int d0 = 0; d0 < 4; ++d0) {
;     const v8i32 vf = cat8(*reinterpret_cast<const v4i32*>(Vt + d0 * 2048 + a0), *reinterpret_cast<const v4i32*>(Vt + d0 * 2048 + a1));
;     o[d0] = __builtin_amdgcn_mfma_scale_f32_32x32x64_f8f6f4(p8, vf, o[d0], 0, 0, 0, 127, 0, 127); }
; }
; __device__ __forceinline__ void qkt9(f32x16& p0, f32x16& p1, const char* Kn, const char* Kr, const v8i32* qf, const float init, int r32, int hi) {
; #pragma unroll
;   for (int r = 0; r < 16; ++r) { p0[r] = init; p1[r] = init; }
; #pragma unroll
;   for (int s = 0; s < 2; ++s) { const int c0 = s * 4 + hi * 2;
;     const v8i32 a0 = cat8(*reinterpret_cast<const v4i32*>(Kn + KN8SW(r32, c0)), *reinterpret_cast<const v4i32*>(Kn + KN8SW(r32, c0 + 1)));
;     const v8i32 a1 = cat8(*reinterpret_cast<const v4i32*>(Kn + 4096 + KN8SW(r32, c0)), *reinterpret_cast<const v4i32*>(Kn + 4096 + KN8SW(r32, c0 + 1)));
;     p0 = __builtin_amdgcn_mfma_scale_f32_32x32x64_f8f6f4(a0, qf[s], p0, 0, 0, 0, 127, 0, 124);
;     p1 = __builtin_amdgcn_mfma_scale_f32_32x32x64_f8f6f4(a1, qf[s], p1, 0, 0, 0, 127, 0, 124); }
;   { const int c0 = hi * 2;
.Lmla_s0_cont:
	ds_read_b128 v[82:85], v215 offset:51200
	ds_read_b128 v[86:89], v216 offset:51200
	ds_read_b128 v[222:225], v215 offset:55296
	ds_read_b128 v[226:229], v216 offset:55296
	v_exp_f32_e32 v0, v114
	v_exp_f32_e32 v177, v115
	v_exp_f32_e32 v179, v116
	v_exp_f32_e32 v254, v117
	v_add_f32_e32 v219, v0, v177
	v_cvt_pk_fp8_f32 v246, v0, v177
	v_add_f32_e32 v219, v179, v219
	v_add_f32_e32 v219, v254, v219
	v_cvt_pk_fp8_f32 v246, v179, v254 op_sel:[0,0,1]
	s_waitcnt lgkmcnt(2)
	v_mfma_scale_f32_32x32x64_f8f6f4 v[82:97], v[82:89], v[146:153], v[230:245], v194, v193 op_sel_hi:[0,0,0]
	v_exp_f32_e32 v0, v118
	v_exp_f32_e32 v177, v119
	v_exp_f32_e32 v179, v120
	v_exp_f32_e32 v254, v121
	v_add_f32_e32 v219, v0, v219
	v_add_f32_e32 v219, v177, v219
	v_cvt_pk_fp8_f32 v247, v0, v177
	v_add_f32_e32 v219, v179, v219
	v_add_f32_e32 v219, v254, v219
	v_cvt_pk_fp8_f32 v247, v179, v254 op_sel:[0,0,1]
	ds_read_b128 v[114:117], v213 offset:51200
	ds_read_b128 v[118:121], v214 offset:51200
	s_waitcnt lgkmcnt(2)
	v_mfma_scale_f32_32x32x64_f8f6f4 v[66:81], v[222:229], v[146:153], v[230:245], v194, v193 op_sel_hi:[0,0,0]
	ds_read_b128 v[222:225], v213 offset:55296
	ds_read_b128 v[226:229], v214 offset:55296
	v_exp_f32_e32 v0, v122
	v_exp_f32_e32 v177, v123
	v_exp_f32_e32 v179, v124
	v_exp_f32_e32 v254, v125
	v_add_f32_e32 v219, v0, v219
	v_add_f32_e32 v219, v177, v219
	v_cvt_pk_fp8_f32 v248, v0, v177
	v_add_f32_e32 v219, v179, v219
	v_add_f32_e32 v219, v254, v219
	v_cvt_pk_fp8_f32 v248, v179, v254 op_sel:[0,0,1]
	v_exp_f32_e32 v0, v126
	v_exp_f32_e32 v177, v127
	v_exp_f32_e32 v179, v128
	v_exp_f32_e32 v254, v129
	v_add_f32_e32 v219, v0, v219
	v_add_f32_e32 v219, v177, v219
	v_cvt_pk_fp8_f32 v249, v0, v177
	v_add_f32_e32 v219, v179, v219
	v_add_f32_e32 v219, v254, v219
	v_cvt_pk_fp8_f32 v249, v179, v254 op_sel:[0,0,1]
	ds_read_b128 v[122:125], v185 offset:59392
	ds_read_b128 v[126:129], v186 offset:59392
	s_waitcnt lgkmcnt(4)
	v_mfma_scale_f32_32x32x64_f8f6f4 v[82:97], v[114:121], v[138:145], v[82:97], v194, v193 op_sel_hi:[0,0,0]
	v_exp_f32_e32 v0, v98
	v_exp_f32_e32 v177, v99
	v_exp_f32_e32 v179, v100
	v_exp_f32_e32 v254, v101
	v_add_f32_e32 v219, v0, v219
	v_add_f32_e32 v219, v177, v219
	v_cvt_pk_fp8_f32 v250, v0, v177
	v_add_f32_e32 v219, v179, v219
	v_add_f32_e32 v219, v254, v219
	v_cvt_pk_fp8_f32 v250, v179, v254 op_sel:[0,0,1]
	s_waitcnt lgkmcnt(2)
	v_mfma_scale_f32_32x32x64_f8f6f4 v[66:81], v[222:229], v[138:145], v[66:81], v194, v193 op_sel_hi:[0,0,0]
	ds_read_b128 v[222:225], v185 offset:61440
	ds_read_b128 v[226:229], v186 offset:61440
	v_exp_f32_e32 v0, v102
	v_exp_f32_e32 v177, v103
	v_exp_f32_e32 v179, v104
	v_exp_f32_e32 v254, v105
	v_add_f32_e32 v219, v0, v219
	v_add_f32_e32 v219, v177, v219
	v_cvt_pk_fp8_f32 v251, v0, v177
	v_add_f32_e32 v219, v179, v219
	v_add_f32_e32 v219, v254, v219
	v_cvt_pk_fp8_f32 v251, v179, v254 op_sel:[0,0,1]
	v_exp_f32_e32 v0, v106
	v_exp_f32_e32 v177, v107
	v_exp_f32_e32 v179, v108
	v_exp_f32_e32 v254, v109
	v_add_f32_e32 v219, v0, v219
	v_add_f32_e32 v219, v177, v219
	v_cvt_pk_fp8_f32 v252, v0, v177
	v_add_f32_e32 v219, v179, v219
	v_add_f32_e32 v219, v254, v219
	v_cvt_pk_fp8_f32 v252, v179, v254 op_sel:[0,0,1]
	s_waitcnt lgkmcnt(2)
	v_mfma_scale_f32_32x32x64_f8f6f4 v[82:97], v[122:129], v[130:137], v[82:97], v194, v193 op_sel_hi:[0,0,0]
	v_exp_f32_e32 v0, v110
	v_exp_f32_e32 v177, v111
	v_exp_f32_e32 v179, v112
	v_exp_f32_e32 v254, v113
	v_add_f32_e32 v219, v0, v219
	v_add_f32_e32 v219, v177, v219
	v_cvt_pk_fp8_f32 v253, v0, v177
	v_add_f32_e32 v219, v179, v219
	v_add_f32_e32 v219, v254, v219
	v_cvt_pk_fp8_f32 v253, v179, v254 op_sel:[0,0,1]
	ds_read_b128 v[122:125], v185 offset:8192
	ds_read_b128 v[126:129], v186 offset:8192
	ds_read_b128 v[114:117], v185 offset:10240
	ds_read_b128 v[118:121], v186 offset:10240
	ds_read_b128 v[106:109], v185 offset:12288
	ds_read_b128 v[110:113], v186 offset:12288
	ds_read_b128 v[98:101], v185 offset:14336
	ds_read_b128 v[102:105], v186 offset:14336
	s_waitcnt lgkmcnt(8)
	v_mfma_scale_f32_32x32x64_f8f6f4 v[66:81], v[222:229], v[130:137], v[66:81], v194, v193 op_sel_hi:[0,0,0]
	v_mov_b32_e32 v0, v219
	s_nop 1
	v_permlane32_swap_b32_e32 v219, v0
	v_add_f32_e32 v219, v219, v0
	v_fma_f32 v209, v209, v221, v219
	v_max_f32_e32 v177, v82, v83
	v_max3_f32 v177, v177, v84, v85
	v_max3_f32 v177, v177, v86, v87
	v_max3_f32 v177, v177, v88, v89
	v_max3_f32 v177, v177, v90, v91
	v_max3_f32 v177, v177, v92, v93
	v_max3_f32 v177, v177, v94, v95
	v_max3_f32 v177, v177, v96, v97
	s_waitcnt lgkmcnt(6)
	v_mfma_scale_f32_32x32x64_f8f6f4 v[50:65], v[246:253], v[122:129], v[50:65], v194, v194 op_sel_hi:[0,0,0]
	s_waitcnt lgkmcnt(4)
	v_mfma_scale_f32_32x32x64_f8f6f4 v[34:49], v[246:253], v[114:121], v[34:49], v194, v194 op_sel_hi:[0,0,0]
	s_waitcnt lgkmcnt(2)
	v_mfma_scale_f32_32x32x64_f8f6f4 v[18:33], v[246:253], v[106:113], v[18:33], v194, v194 op_sel_hi:[0,0,0]
	s_waitcnt vmcnt(0)
	s_waitcnt lgkmcnt(0)
	s_barrier
	s_waitcnt lgkmcnt(0)
	v_mfma_scale_f32_32x32x64_f8f6f4 v[2:17], v[246:253], v[98:105], v[2:17], v194, v194 op_sel_hi:[0,0,0]
	s_add_i32 m0, s98, 0x2000
	s_nop 0
	global_load_lds_dwordx4 v176, s[18:19]
	s_add_i32 m0, s98, 0x6000
	s_nop 0
	global_load_lds_dwordx4 v178, s[16:17]
	v_add_u32_e32 v176, 0x2000, v176
	v_add_u32_e32 v178, 0x20000, v178
	v_max_f32_e32 v0, v66, v67
	v_max3_f32 v0, v0, v68, v69
	v_max3_f32 v0, v0, v70, v71
	v_max3_f32 v0, v0, v72, v73
	v_max3_f32 v0, v0, v74, v75
	v_max3_f32 v0, v0, v76, v77
	v_max3_f32 v0, v0, v78, v79
	v_max3_f32 v0, v0, v80, v81
	v_max_f32_e32 v177, v177, v0
	v_mov_b32_e32 v0, v177
	v_mov_b32_e32 v218, 1.0
	s_nop 0
	v_permlane32_swap_b32_e32 v177, v0
	v_max_f32_e32 v177, v177, v0
	v_cmp_ge_f32_e32 vcc, s90, v177
	s_cmp_eq_u64 vcc, exec
	s_cbranch_scc0 .Lmla_s1_newmax
; __device__ __forceinline__ void finishSM9(f32x16& p0, f32x16& p1, float alpha, float& l_reg, v8i32& p8) {
; #pragma unroll
;   for (int r = 0; r < 16; ++r) { p0[r] = __builtin_amdgcn_exp2f(p0[r]); p1[r] = __builtin_amdgcn_exp2f(p1[r]); }
;   float ps = 0;
; #pragma unroll
;   for (int r = 0; r < 16; ++r) ps += p0[r];
; #pragma unroll
;   for (int r = 0; r < 16; ++r) ps += p1[r];
;   { auto rr = __builtin_amdgcn_permlane32_swap(__float_as_uint(ps), __float_as_uint(ps), false, false);
;     ps = __uint_as_float(rr[0]) + __uint_as_float(rr[1]); }
;   l_reg = l_reg * alpha + ps;
; #pragma unroll
;   for (int g = 0; g < 4; ++g) {
;     int w = __builtin_amdgcn_cvt_pk_fp8_f32(p0[4 * g], p0[4 * g + 1], 0, false); p8[g] = __builtin_amdgcn_cvt_pk_fp8_f32(p0[4 * g + 2], p0[4 * g + 3], w, true);
;     int u = __builtin_amdgcn_cvt_pk_fp8_f32(p1[4 * g], p1[4 * g + 1], 0, false); p8[4 + g] = __builtin_amdgcn_cvt_pk_fp8_f32(p1[4 * g + 2], p1[4 * g + 3], u, true); }
; }
; __device__ __forceinline__ void pv8(f32x16* o, const char* Vt, const v8i32 p8, int r32, int hi) {
;   const int sw = (r32 >> 2) & 3, a0 = r32 * 64 + (((hi * 2) ^ sw) << 4), a1 = r32 * 64 + (((hi * 2 + 1) ^ sw) << 4);
; #pragma unroll
;   for (int d0 = 0; d0 < 4; ++d0) {
;     const v8i32 vf = cat8(*reinterpret_cast<const v4i32*>(Vt + d0 * 2048 + a0), *reinterpret_cast<const v4i32*>(Vt + d0 * 2048 + a1));
;     o[d0] = __builtin_amdgcn_mfma_scale_f32_32x32x64_f8f6f4(p8, vf, o[d0], 0, 0, 0, 127, 0, 127); }
; }
; __device__ __forceinline__ void qkt9(f32x16& p0, f32x16& p1, const char* Kn, const char* Kr, const v8i32* qf, const float init, int r32, int hi) {
; #pragma unroll
;   for (int r = 0; r < 16; ++r) { p0[r] = init; p1[r] = init; }
; #pragma unroll
;   for (int s = 0; s < 2; ++s) { const int c0 = s * 4 + hi * 2;
;     const v8i32 a0 = cat8(*reinterpret_cast<const v4i32*>(Kn + KN8SW(r32, c0)), *reinterpret_cast<const v4i32*>(Kn + KN8SW(r32, c0 + 1)));
;     const v8i32 a1 = cat8(*reinterpret_cast<const v4i32*>(Kn + 4096 + KN8SW(r32, c0)), *reinterpret_cast<const v4i32*>(Kn + 4096 + KN8SW(r32, c0 + 1)));
;     p0 = __builtin_amdgcn_mfma_scale_f32_32x32x64_f8f6f4(a0, qf[s], p0, 0, 0, 0, 127, 0, 124);
;     p1 = __builtin_amdgcn_mfma_scale_f32_32x32x64_f8f6f4(a1, qf[s], p1, 0, 0, 0, 127, 0, 124); }
;   { const int c0 = hi * 2;
.Lmla_s1_cont:
	ds_read_b128 v[114:117], v215 offset:16384
	ds_read_b128 v[118:121], v216 offset:16384
	ds_read_b128 v[222:225], v215 offset:20480
	ds_read_b128 v[226:229], v216 offset:20480
	v_exp_f32_e32 v0, v82
	v_exp_f32_e32 v177, v83
	v_exp_f32_e32 v179, v84
	v_exp_f32_e32 v254, v85
	v_add_f32_e32 v219, v0, v177
	v_cvt_pk_fp8_f32 v246, v0, v177
	v_add_f32_e32 v219, v179, v219
	v_add_f32_e32 v219, v254, v219
	v_cvt_pk_fp8_f32 v246, v179, v254 op_sel:[0,0,1]
	s_waitcnt lgkmcnt(2)
	v_mfma_scale_f32_32x32x64_f8f6f4 v[114:129], v[114:121], v[146:153], v[230:245], v194, v193 op_sel_hi:[0,0,0]
	v_exp_f32_e32 v0, v86
	v_exp_f32_e32 v177, v87
	v_exp_f32_e32 v179, v88
	v_exp_f32_e32 v254, v89
	v_add_f32_e32 v219, v0, v219
	v_add_f32_e32 v219, v177, v219
	v_cvt_pk_fp8_f32 v247, v0, v177
	v_add_f32_e32 v219, v179, v219
	v_add_f32_e32 v219, v254, v219
	v_cvt_pk_fp8_f32 v247, v179, v254 op_sel:[0,0,1]
	ds_read_b128 v[82:85], v213 offset:16384
	ds_read_b128 v[86:89], v214 offset:16384
	s_waitcnt lgkmcnt(2)
	v_mfma_scale_f32_32x32x64_f8f6f4 v[98:113], v[222:229], v[146:153], v[230:245], v194, v193 op_sel_hi:[0,0,0]
	ds_read_b128 v[222:225], v213 offset:20480
	ds_read_b128 v[226:229], v214 offset:20480
	v_exp_f32_e32 v0, v90
	v_exp_f32_e32 v177, v91
	v_exp_f32_e32 v179, v92
	v_exp_f32_e32 v254, v93
	v_add_f32_e32 v219, v0, v219
	v_add_f32_e32 v219, v177, v219
	v_cvt_pk_fp8_f32 v248, v0, v177
	v_add_f32_e32 v219, v179, v219
	v_add_f32_e32 v219, v254, v219
	v_cvt_pk_fp8_f32 v248, v179, v254 op_sel:[0,0,1]
	v_exp_f32_e32 v0, v94
	v_exp_f32_e32 v177, v95
	v_exp_f32_e32 v179, v96
	v_exp_f32_e32 v254, v97
	v_add_f32_e32 v219, v0, v219
	v_add_f32_e32 v219, v177, v219
	v_cvt_pk_fp8_f32 v249, v0, v177
	v_add_f32_e32 v219, v179, v219
	v_add_f32_e32 v219, v254, v219
	v_cvt_pk_fp8_f32 v249, v179, v254 op_sel:[0,0,1]
	ds_read_b128 v[90:93], v185 offset:32768
	ds_read_b128 v[94:97], v186 offset:32768
	s_waitcnt lgkmcnt(4)
	v_mfma_scale_f32_32x32x64_f8f6f4 v[114:129], v[82:89], v[138:145], v[114:129], v194, v193 op_sel_hi:[0,0,0]
	v_exp_f32_e32 v0, v66
	v_exp_f32_e32 v177, v67
	v_exp_f32_e32 v179, v68
	v_exp_f32_e32 v254, v69
	v_add_f32_e32 v219, v0, v219
	v_add_f32_e32 v219, v177, v219
	v_cvt_pk_fp8_f32 v250, v0, v177
	v_add_f32_e32 v219, v179, v219
	v_add_f32_e32 v219, v254, v219
	v_cvt_pk_fp8_f32 v250, v179, v254 op_sel:[0,0,1]
	s_waitcnt lgkmcnt(2)
	v_mfma_scale_f32_32x32x64_f8f6f4 v[98:113], v[222:229], v[138:145], v[98:113], v194, v193 op_sel_hi:[0,0,0]
	ds_read_b128 v[222:225], v185 offset:34816
	ds_read_b128 v[226:229], v186 offset:34816
	v_exp_f32_e32 v0, v70
	v_exp_f32_e32 v177, v71
	v_exp_f32_e32 v179, v72
	v_exp_f32_e32 v254, v73
	v_add_f32_e32 v219, v0, v219
	v_add_f32_e32 v219, v177, v219
	v_cvt_pk_fp8_f32 v251, v0, v177
	v_add_f32_e32 v219, v179, v219
	v_add_f32_e32 v219, v254, v219
	v_cvt_pk_fp8_f32 v251, v179, v254 op_sel:[0,0,1]
	v_exp_f32_e32 v0, v74
	v_exp_f32_e32 v177, v75
	v_exp_f32_e32 v179, v76
	v_exp_f32_e32 v254, v77
	v_add_f32_e32 v219, v0, v219
	v_add_f32_e32 v219, v177, v219
	v_cvt_pk_fp8_f32 v252, v0, v177
	v_add_f32_e32 v219, v179, v219
	v_add_f32_e32 v219, v254, v219
	v_cvt_pk_fp8_f32 v252, v179, v254 op_sel:[0,0,1]
	s_waitcnt lgkmcnt(2)
	v_mfma_scale_f32_32x32x64_f8f6f4 v[114:129], v[90:97], v[130:137], v[114:129], v194, v193 op_sel_hi:[0,0,0]
	v_exp_f32_e32 v0, v78
	v_exp_f32_e32 v177, v79
	v_exp_f32_e32 v179, v80
	v_exp_f32_e32 v254, v81
	v_add_f32_e32 v219, v0, v219
	v_add_f32_e32 v219, v177, v219
	v_cvt_pk_fp8_f32 v253, v0, v177
	v_add_f32_e32 v219, v179, v219
	v_add_f32_e32 v219, v254, v219
	v_cvt_pk_fp8_f32 v253, v179, v254 op_sel:[0,0,1]
	ds_read_b128 v[90:93], v185 offset:43008
	ds_read_b128 v[94:97], v186 offset:43008
	ds_read_b128 v[82:85], v185 offset:45056
	ds_read_b128 v[86:89], v186 offset:45056
	ds_read_b128 v[74:77], v185 offset:47104
	ds_read_b128 v[78:81], v186 offset:47104
	ds_read_b128 v[66:69], v185 offset:49152
	ds_read_b128 v[70:73], v186 offset:49152
	s_waitcnt lgkmcnt(8)
	v_mfma_scale_f32_32x32x64_f8f6f4 v[98:113], v[222:229], v[130:137], v[98:113], v194, v193 op_sel_hi:[0,0,0]
	v_mov_b32_e32 v0, v219
	s_nop 1
	v_permlane32_swap_b32_e32 v219, v0
	v_add_f32_e32 v219, v219, v0
	v_fma_f32 v209, v209, v218, v219
	v_max_f32_e32 v177, v114, v115
	v_max3_f32 v177, v177, v116, v117
	v_max3_f32 v177, v177, v118, v119
	v_max3_f32 v177, v177, v120, v121
	v_max3_f32 v177, v177, v122, v123
	v_max3_f32 v177, v177, v124, v125
	v_max3_f32 v177, v177, v126, v127
	v_max3_f32 v177, v177, v128, v129
	s_waitcnt lgkmcnt(6)
	v_mfma_scale_f32_32x32x64_f8f6f4 v[50:65], v[246:253], v[90:97], v[50:65], v194, v194 op_sel_hi:[0,0,0]
	s_waitcnt lgkmcnt(4)
	v_mfma_scale_f32_32x32x64_f8f6f4 v[34:49], v[246:253], v[82:89], v[34:49], v194, v194 op_sel_hi:[0,0,0]
	s_waitcnt lgkmcnt(2)
	v_mfma_scale_f32_32x32x64_f8f6f4 v[18:33], v[246:253], v[74:81], v[18:33], v194, v194 op_sel_hi:[0,0,0]
	s_waitcnt vmcnt(0)
	s_waitcnt lgkmcnt(0)
	s_barrier
	s_waitcnt lgkmcnt(0)
	v_mfma_scale_f32_32x32x64_f8f6f4 v[2:17], v[246:253], v[66:73], v[2:17], v194, v194 op_sel_hi:[0,0,0]
	s_add_i32 m0, s98, 0xa800
	s_nop 0
	global_load_lds_dwordx4 v176, s[18:19]
	s_add_i32 m0, s98, 0xc800
	s_nop 0
	global_load_lds_dwordx4 v178, s[16:17]
	v_add_u32_e32 v176, 0x2000, v176
	v_add_u32_e32 v178, 0x20000, v178
	v_max_f32_e32 v0, v98, v99
	v_max3_f32 v0, v0, v100, v101
	v_max3_f32 v0, v0, v102, v103
	v_max3_f32 v0, v0, v104, v105
	v_max3_f32 v0, v0, v106, v107
	v_max3_f32 v0, v0, v108, v109
	v_max3_f32 v0, v0, v110, v111
	v_max3_f32 v0, v0, v112, v113
	v_max_f32_e32 v177, v177, v0
	v_mov_b32_e32 v0, v177
	v_mov_b32_e32 v221, 1.0
	s_nop 0
	v_permlane32_swap_b32_e32 v177, v0
	v_max_f32_e32 v177, v177, v0
	v_cmp_ge_f32_e32 vcc, s90, v177
	s_cmp_eq_u64 vcc, exec
	s_cbranch_scc0 .Lmla_s2_newmax
; __device__ __forceinline__ void finishSM9(f32x16& p0, f32x16& p1, float alpha, float& l_reg, v8i32& p8) {
; #pragma unroll
;   for (int r = 0; r < 16; ++r) { p0[r] = __builtin_amdgcn_exp2f(p0[r]); p1[r] = __builtin_amdgcn_exp2f(p1[r]); }
;   float ps = 0;
; #pragma unroll
;   for (int r = 0; r < 16; ++r) ps += p0[r];
; #pragma unroll
;   for (int r = 0; r < 16; ++r) ps += p1[r];
;   { auto rr = __builtin_amdgcn_permlane32_swap(__float_as_uint(ps), __float_as_uint(ps), false, false);
;     ps = __uint_as_float(rr[0]) + __uint_as_float(rr[1]); }
;   l_reg = l_reg * alpha + ps;
; #pragma unroll
;   for (int g = 0; g < 4; ++g) {
;     int w = __builtin_amdgcn_cvt_pk_fp8_f32(p0[4 * g], p0[4 * g + 1], 0, false); p8[g] = __builtin_amdgcn_cvt_pk_fp8_f32(p0[4 * g + 2], p0[4 * g + 3], w, true);
;     int u = __builtin_amdgcn_cvt_pk_fp8_f32(p1[4 * g], p1[4 * g + 1], 0, false); p8[4 + g] = __builtin_amdgcn_cvt_pk_fp8_f32(p1[4 * g + 2], p1[4 * g + 3], u, true); }
; }
; __device__ __forceinline__ void pv8(f32x16* o, const char* Vt, const v8i32 p8, int r32, int hi) {
;   const int sw = (r32 >> 2) & 3, a0 = r32 * 64 + (((hi * 2) ^ sw) << 4), a1 = r32 * 64 + (((hi * 2 + 1) ^ sw) << 4);
; #pragma unroll
;   for (int d0 = 0; d0 < 4; ++d0) {
;     const v8i32 vf = cat8(*reinterpret_cast<const v4i32*>(Vt + d0 * 2048 + a0), *reinterpret_cast<const v4i32*>(Vt + d0 * 2048 + a1));
;     o[d0] = __builtin_amdgcn_mfma_scale_f32_32x32x64_f8f6f4(p8, vf, o[d0], 0, 0, 0, 127, 0, 127); }
; }
; __device__ __forceinline__ void qkt9(f32x16& p0, f32x16& p1, const char* Kn, const char* Kr, const v8i32* qf, const float init, int r32, int hi) {
; #pragma unroll
;   for (int r = 0; r < 16; ++r) { p0[r] = init; p1[r] = init; }
; #pragma unroll
;   for (int s = 0; s < 2; ++s) { const int c0 = s * 4 + hi * 2;
;     const v8i32 a0 = cat8(*reinterpret_cast<const v4i32*>(Kn + KN8SW(r32, c0)), *reinterpret_cast<const v4i32*>(Kn + KN8SW(r32, c0 + 1)));
;     const v8i32 a1 = cat8(*reinterpret_cast<const v4i32*>(Kn + 4096 + KN8SW(r32, c0)), *reinterpret_cast<const v4i32*>(Kn + 4096 + KN8SW(r32, c0 + 1)));
;     p0 = __builtin_amdgcn_mfma_scale_f32_32x32x64_f8f6f4(a0, qf[s], p0, 0, 0, 0, 127, 0, 124);
;     p1 = __builtin_amdgcn_mfma_scale_f32_32x32x64_f8f6f4(a1, qf[s], p1, 0, 0, 0, 127, 0, 124); }
;   { const int c0 = hi * 2;
.Lmla_s2_cont:
	ds_read_b128 v[82:85], v215 offset:24576
	ds_read_b128 v[86:89], v216 offset:24576
	ds_read_b128 v[222:225], v215 offset:28672
	ds_read_b128 v[226:229], v216 offset:28672
	v_exp_f32_e32 v0, v114
	v_exp_f32_e32 v177, v115
	v_exp_f32_e32 v179, v116
	v_exp_f32_e32 v254, v117
	v_add_f32_e32 v219, v0, v177
	v_cvt_pk_fp8_f32 v246, v0, v177
	v_add_f32_e32 v219, v179, v219
	v_add_f32_e32 v219, v254, v219
	v_cvt_pk_fp8_f32 v246, v179, v254 op_sel:[0,0,1]
	s_waitcnt lgkmcnt(2)
	v_mfma_scale_f32_32x32x64_f8f6f4 v[82:97], v[82:89], v[146:153], v[230:245], v194, v193 op_sel_hi:[0,0,0]
	v_exp_f32_e32 v0, v118
	v_exp_f32_e32 v177, v119
	v_exp_f32_e32 v179, v120
	v_exp_f32_e32 v254, v121
	v_add_f32_e32 v219, v0, v219
	v_add_f32_e32 v219, v177, v219
	v_cvt_pk_fp8_f32 v247, v0, v177
	v_add_f32_e32 v219, v179, v219
	v_add_f32_e32 v219, v254, v219
	v_cvt_pk_fp8_f32 v247, v179, v254 op_sel:[0,0,1]
	ds_read_b128 v[114:117], v213 offset:24576
	ds_read_b128 v[118:121], v214 offset:24576
	s_waitcnt lgkmcnt(2)
	v_mfma_scale_f32_32x32x64_f8f6f4 v[66:81], v[222:229], v[146:153], v[230:245], v194, v193 op_sel_hi:[0,0,0]
	ds_read_b128 v[222:225], v213 offset:28672
	ds_read_b128 v[226:229], v214 offset:28672
	v_exp_f32_e32 v0, v122
	v_exp_f32_e32 v177, v123
	v_exp_f32_e32 v179, v124
	v_exp_f32_e32 v254, v125
	v_add_f32_e32 v219, v0, v219
	v_add_f32_e32 v219, v177, v219
	v_cvt_pk_fp8_f32 v248, v0, v177
	v_add_f32_e32 v219, v179, v219
	v_add_f32_e32 v219, v254, v219
	v_cvt_pk_fp8_f32 v248, v179, v254 op_sel:[0,0,1]
	v_exp_f32_e32 v0, v126
	v_exp_f32_e32 v177, v127
	v_exp_f32_e32 v179, v128
	v_exp_f32_e32 v254, v129
	v_add_f32_e32 v219, v0, v219
	v_add_f32_e32 v219, v177, v219
	v_cvt_pk_fp8_f32 v249, v0, v177
	v_add_f32_e32 v219, v179, v219
	v_add_f32_e32 v219, v254, v219
	v_cvt_pk_fp8_f32 v249, v179, v254 op_sel:[0,0,1]
	ds_read_b128 v[122:125], v185 offset:36864
	ds_read_b128 v[126:129], v186 offset:36864
	s_waitcnt lgkmcnt(4)
	v_mfma_scale_f32_32x32x64_f8f6f4 v[82:97], v[114:121], v[138:145], v[82:97], v194, v193 op_sel_hi:[0,0,0]
	v_exp_f32_e32 v0, v98
	v_exp_f32_e32 v177, v99
	v_exp_f32_e32 v179, v100
	v_exp_f32_e32 v254, v101
	v_add_f32_e32 v219, v0, v219
	v_add_f32_e32 v219, v177, v219
	v_cvt_pk_fp8_f32 v250, v0, v177
	v_add_f32_e32 v219, v179, v219
	v_add_f32_e32 v219, v254, v219
	v_cvt_pk_fp8_f32 v250, v179, v254 op_sel:[0,0,1]
	s_waitcnt lgkmcnt(2)
	v_mfma_scale_f32_32x32x64_f8f6f4 v[66:81], v[222:229], v[138:145], v[66:81], v194, v193 op_sel_hi:[0,0,0]
	ds_read_b128 v[222:225], v185 offset:38912
	ds_read_b128 v[226:229], v186 offset:38912
	v_exp_f32_e32 v0, v102
	v_exp_f32_e32 v177, v103
	v_exp_f32_e32 v179, v104
	v_exp_f32_e32 v254, v105
	v_add_f32_e32 v219, v0, v219
	v_add_f32_e32 v219, v177, v219
	v_cvt_pk_fp8_f32 v251, v0, v177
	v_add_f32_e32 v219, v179, v219
	v_add_f32_e32 v219, v254, v219
	v_cvt_pk_fp8_f32 v251, v179, v254 op_sel:[0,0,1]
	v_exp_f32_e32 v0, v106
	v_exp_f32_e32 v177, v107
	v_exp_f32_e32 v179, v108
	v_exp_f32_e32 v254, v109
	v_add_f32_e32 v219, v0, v219
	v_add_f32_e32 v219, v177, v219
	v_cvt_pk_fp8_f32 v252, v0, v177
	v_add_f32_e32 v219, v179, v219
	v_add_f32_e32 v219, v254, v219
	v_cvt_pk_fp8_f32 v252, v179, v254 op_sel:[0,0,1]
	s_waitcnt lgkmcnt(2)
	v_mfma_scale_f32_32x32x64_f8f6f4 v[82:97], v[122:129], v[130:137], v[82:97], v194, v193 op_sel_hi:[0,0,0]
	v_exp_f32_e32 v0, v110
	v_exp_f32_e32 v177, v111
	v_exp_f32_e32 v179, v112
	v_exp_f32_e32 v254, v113
	v_add_f32_e32 v219, v0, v219
	v_add_f32_e32 v219, v177, v219
	v_cvt_pk_fp8_f32 v253, v0, v177
	v_add_f32_e32 v219, v179, v219
	v_add_f32_e32 v219, v254, v219
	v_cvt_pk_fp8_f32 v253, v179, v254 op_sel:[0,0,1]
	ds_read_b128 v[122:125], v185 offset:0
	ds_read_b128 v[126:129], v186 offset:0
	ds_read_b128 v[114:117], v185 offset:2048
	ds_read_b128 v[118:121], v186 offset:2048
	ds_read_b128 v[106:109], v185 offset:4096
	ds_read_b128 v[110:113], v186 offset:4096
	ds_read_b128 v[98:101], v185 offset:6144
	ds_read_b128 v[102:105], v186 offset:6144
	s_waitcnt lgkmcnt(8)
	v_mfma_scale_f32_32x32x64_f8f6f4 v[66:81], v[222:229], v[130:137], v[66:81], v194, v193 op_sel_hi:[0,0,0]
	v_mov_b32_e32 v0, v219
	s_nop 1
	v_permlane32_swap_b32_e32 v219, v0
	v_add_f32_e32 v219, v219, v0
	v_fma_f32 v209, v209, v221, v219
	v_max_f32_e32 v177, v82, v83
	v_max3_f32 v177, v177, v84, v85
	v_max3_f32 v177, v177, v86, v87
	v_max3_f32 v177, v177, v88, v89
	v_max3_f32 v177, v177, v90, v91
	v_max3_f32 v177, v177, v92, v93
	v_max3_f32 v177, v177, v94, v95
	v_max3_f32 v177, v177, v96, v97
	s_waitcnt lgkmcnt(6)
	v_mfma_scale_f32_32x32x64_f8f6f4 v[50:65], v[246:253], v[122:129], v[50:65], v194, v194 op_sel_hi:[0,0,0]
	s_waitcnt lgkmcnt(4)
	v_mfma_scale_f32_32x32x64_f8f6f4 v[34:49], v[246:253], v[114:121], v[34:49], v194, v194 op_sel_hi:[0,0,0]
	s_waitcnt lgkmcnt(2)
	v_mfma_scale_f32_32x32x64_f8f6f4 v[18:33], v[246:253], v[106:113], v[18:33], v194, v194 op_sel_hi:[0,0,0]
	s_waitcnt vmcnt(0)
	s_waitcnt lgkmcnt(0)
	s_barrier
	s_waitcnt lgkmcnt(0)
	v_mfma_scale_f32_32x32x64_f8f6f4 v[2:17], v[246:253], v[98:105], v[2:17], v194, v194 op_sel_hi:[0,0,0]
	s_add_i32 m0, s98, 0x0
	s_nop 0
	global_load_lds_dwordx4 v176, s[18:19]
	s_add_i32 m0, s98, 0x4000
	s_nop 0
	global_load_lds_dwordx4 v178, s[16:17]
	v_add_u32_e32 v176, 0x2000, v176
	v_add_u32_e32 v178, 0x20000, v178
	v_max_f32_e32 v0, v66, v67
	v_max3_f32 v0, v0, v68, v69
	v_max3_f32 v0, v0, v70, v71
	v_max3_f32 v0, v0, v72, v73
	v_max3_f32 v0, v0, v74, v75
	v_max3_f32 v0, v0, v76, v77
	v_max3_f32 v0, v0, v78, v79
	v_max3_f32 v0, v0, v80, v81
	v_max_f32_e32 v177, v177, v0
	v_mov_b32_e32 v0, v177
	v_mov_b32_e32 v218, 1.0
	s_nop 0
	v_permlane32_swap_b32_e32 v177, v0
	v_max_f32_e32 v177, v177, v0
	v_cmp_ge_f32_e32 vcc, s90, v177
	s_cmp_eq_u64 vcc, exec
	s_cbranch_scc0 .Lmla_s3_newmax
; __device__ __forceinline__ void finishSM9(f32x16& p0, f32x16& p1, float alpha, float& l_reg, v8i32& p8) {
; #pragma unroll
;   for (int r = 0; r < 16; ++r) { p0[r] = __builtin_amdgcn_exp2f(p0[r]); p1[r] = __builtin_amdgcn_exp2f(p1[r]); }
;   float ps = 0;
; #pragma unroll
;   for (int r = 0; r < 16; ++r) ps += p0[r];
; #pragma unroll
;   for (int r = 0; r < 16; ++r) ps += p1[r];
;   { auto rr = __builtin_amdgcn_permlane32_swap(__float_as_uint(ps), __float_as_uint(ps), false, false);
;     ps = __uint_as_float(rr[0]) + __uint_as_float(rr[1]); }
;   l_reg = l_reg * alpha + ps;
; #pragma unroll
;   for (int g = 0; g < 4; ++g) {
;     int w = __builtin_amdgcn_cvt_pk_fp8_f32(p0[4 * g], p0[4 * g + 1], 0, false); p8[g] = __builtin_amdgcn_cvt_pk_fp8_f32(p0[4 * g + 2], p0[4 * g + 3], w, true);
;     int u = __builtin_amdgcn_cvt_pk_fp8_f32(p1[4 * g], p1[4 * g + 1], 0, false); p8[4 + g] = __builtin_amdgcn_cvt_pk_fp8_f32(p1[4 * g + 2], p1[4 * g + 3], u, true); }
; }
; __device__ __forceinline__ void pv8(f32x16* o, const char* Vt, const v8i32 p8, int r32, int hi) {
;   const int sw = (r32 >> 2) & 3, a0 = r32 * 64 + (((hi * 2) ^ sw) << 4), a1 = r32 * 64 + (((hi * 2 + 1) ^ sw) << 4);
; #pragma unroll
;   for (int d0 = 0; d0 < 4; ++d0) {
;     const v8i32 vf = cat8(*reinterpret_cast<const v4i32*>(Vt + d0 * 2048 + a0), *reinterpret_cast<const v4i32*>(Vt + d0 * 2048 + a1));
;     o[d0] = __builtin_amdgcn_mfma_scale_f32_32x32x64_f8f6f4(p8, vf, o[d0], 0, 0, 0, 127, 0, 127); }
; }
; __device__ __forceinline__ void qkt9(f32x16& p0, f32x16& p1, const char* Kn, const char* Kr, const v8i32* qf, const float init, int r32, int hi) {
; #pragma unroll
;   for (int r = 0; r < 16; ++r) { p0[r] = init; p1[r] = init; }
; #pragma unroll
;   for (int s = 0; s < 2; ++s) { const int c0 = s * 4 + hi * 2;
;     const v8i32 a0 = cat8(*reinterpret_cast<const v4i32*>(Kn + KN8SW(r32, c0)), *reinterpret_cast<const v4i32*>(Kn + KN8SW(r32, c0 + 1)));
;     const v8i32 a1 = cat8(*reinterpret_cast<const v4i32*>(Kn + 4096 + KN8SW(r32, c0)), *reinterpret_cast<const v4i32*>(Kn + 4096 + KN8SW(r32, c0 + 1)));
;     p0 = __builtin_amdgcn_mfma_scale_f32_32x32x64_f8f6f4(a0, qf[s], p0, 0, 0, 0, 127, 0, 124);
;     p1 = __builtin_amdgcn_mfma_scale_f32_32x32x64_f8f6f4(a1, qf[s], p1, 0, 0, 0, 127, 0, 124); }
;   { const int c0 = hi * 2;
.Lmla_s3_cont:
	ds_read_b128 v[114:117], v215 offset:51200
	ds_read_b128 v[118:121], v216 offset:51200
	ds_read_b128 v[222:225], v215 offset:55296
	ds_read_b128 v[226:229], v216 offset:55296
	v_exp_f32_e32 v0, v82
	v_exp_f32_e32 v177, v83
	v_exp_f32_e32 v179, v84
	v_exp_f32_e32 v254, v85
	v_add_f32_e32 v219, v0, v177
	v_cvt_pk_fp8_f32 v246, v0, v177
	v_add_f32_e32 v219, v179, v219
	v_add_f32_e32 v219, v254, v219
	v_cvt_pk_fp8_f32 v246, v179, v254 op_sel:[0,0,1]
	s_waitcnt lgkmcnt(2)
	v_mfma_scale_f32_32x32x64_f8f6f4 v[114:129], v[114:121], v[146:153], v[230:245], v194, v193 op_sel_hi:[0,0,0]
	v_exp_f32_e32 v0, v86
	v_exp_f32_e32 v177, v87
	v_exp_f32_e32 v179, v88
	v_exp_f32_e32 v254, v89
	v_add_f32_e32 v219, v0, v219
	v_add_f32_e32 v219, v177, v219
	v_cvt_pk_fp8_f32 v247, v0, v177
	v_add_f32_e32 v219, v179, v219
	v_add_f32_e32 v219, v254, v219
	v_cvt_pk_fp8_f32 v247, v179, v254 op_sel:[0,0,1]
	ds_read_b128 v[82:85], v213 offset:51200
	ds_read_b128 v[86:89], v214 offset:51200
	s_waitcnt lgkmcnt(2)
	v_mfma_scale_f32_32x32x64_f8f6f4 v[98:113], v[222:229], v[146:153], v[230:245], v194, v193 op_sel_hi:[0,0,0]
	ds_read_b128 v[222:225], v213 offset:55296
	ds_read_b128 v[226:229], v214 offset:55296
	v_exp_f32_e32 v0, v90
	v_exp_f32_e32 v177, v91
	v_exp_f32_e32 v179, v92
	v_exp_f32_e32 v254, v93
	v_add_f32_e32 v219, v0, v219
	v_add_f32_e32 v219, v177, v219
	v_cvt_pk_fp8_f32 v248, v0, v177
	v_add_f32_e32 v219, v179, v219
	v_add_f32_e32 v219, v254, v219
	v_cvt_pk_fp8_f32 v248, v179, v254 op_sel:[0,0,1]
	v_exp_f32_e32 v0, v94
	v_exp_f32_e32 v177, v95
	v_exp_f32_e32 v179, v96
	v_exp_f32_e32 v254, v97
	v_add_f32_e32 v219, v0, v219
	v_add_f32_e32 v219, v177, v219
	v_cvt_pk_fp8_f32 v249, v0, v177
	v_add_f32_e32 v219, v179, v219
	v_add_f32_e32 v219, v254, v219
	v_cvt_pk_fp8_f32 v249, v179, v254 op_sel:[0,0,1]
	ds_read_b128 v[90:93], v185 offset:59392
	ds_read_b128 v[94:97], v186 offset:59392
	s_waitcnt lgkmcnt(4)
	v_mfma_scale_f32_32x32x64_f8f6f4 v[114:129], v[82:89], v[138:145], v[114:129], v194, v193 op_sel_hi:[0,0,0]
	v_exp_f32_e32 v0, v66
	v_exp_f32_e32 v177, v67
	v_exp_f32_e32 v179, v68
	v_exp_f32_e32 v254, v69
	v_add_f32_e32 v219, v0, v219
	v_add_f32_e32 v219, v177, v219
	v_cvt_pk_fp8_f32 v250, v0, v177
	v_add_f32_e32 v219, v179, v219
	v_add_f32_e32 v219, v254, v219
	v_cvt_pk_fp8_f32 v250, v179, v254 op_sel:[0,0,1]
	s_waitcnt lgkmcnt(2)
	v_mfma_scale_f32_32x32x64_f8f6f4 v[98:113], v[222:229], v[138:145], v[98:113], v194, v193 op_sel_hi:[0,0,0]
	ds_read_b128 v[222:225], v185 offset:61440
	ds_read_b128 v[226:229], v186 offset:61440
	v_exp_f32_e32 v0, v70
	v_exp_f32_e32 v177, v71
	v_exp_f32_e32 v179, v72
	v_exp_f32_e32 v254, v73
	v_add_f32_e32 v219, v0, v219
	v_add_f32_e32 v219, v177, v219
	v_cvt_pk_fp8_f32 v251, v0, v177
	v_add_f32_e32 v219, v179, v219
	v_add_f32_e32 v219, v254, v219
	v_cvt_pk_fp8_f32 v251, v179, v254 op_sel:[0,0,1]
	v_exp_f32_e32 v0, v74
	v_exp_f32_e32 v177, v75
	v_exp_f32_e32 v179, v76
	v_exp_f32_e32 v254, v77
	v_add_f32_e32 v219, v0, v219
	v_add_f32_e32 v219, v177, v219
	v_cvt_pk_fp8_f32 v252, v0, v177
	v_add_f32_e32 v219, v179, v219
	v_add_f32_e32 v219, v254, v219
	v_cvt_pk_fp8_f32 v252, v179, v254 op_sel:[0,0,1]
	s_waitcnt lgkmcnt(2)
	v_mfma_scale_f32_32x32x64_f8f6f4 v[114:129], v[90:97], v[130:137], v[114:129], v194, v193 op_sel_hi:[0,0,0]
	v_exp_f32_e32 v0, v78
	v_exp_f32_e32 v177, v79
	v_exp_f32_e32 v179, v80
	v_exp_f32_e32 v254, v81
	v_add_f32_e32 v219, v0, v219
	v_add_f32_e32 v219, v177, v219
	v_cvt_pk_fp8_f32 v253, v0, v177
	v_add_f32_e32 v219, v179, v219
	v_add_f32_e32 v219, v254, v219
	v_cvt_pk_fp8_f32 v253, v179, v254 op_sel:[0,0,1]
	ds_read_b128 v[90:93], v185 offset:8192
	ds_read_b128 v[94:97], v186 offset:8192
	ds_read_b128 v[82:85], v185 offset:10240
	ds_read_b128 v[86:89], v186 offset:10240
	ds_read_b128 v[74:77], v185 offset:12288
	ds_read_b128 v[78:81], v186 offset:12288
	ds_read_b128 v[66:69], v185 offset:14336
	ds_read_b128 v[70:73], v186 offset:14336
	s_waitcnt lgkmcnt(8)
	v_mfma_scale_f32_32x32x64_f8f6f4 v[98:113], v[222:229], v[130:137], v[98:113], v194, v193 op_sel_hi:[0,0,0]
	v_mov_b32_e32 v0, v219
	s_nop 1
	v_permlane32_swap_b32_e32 v219, v0
	v_add_f32_e32 v219, v219, v0
	v_fma_f32 v209, v209, v218, v219
	v_max_f32_e32 v177, v114, v115
	v_max3_f32 v177, v177, v116, v117
	v_max3_f32 v177, v177, v118, v119
	v_max3_f32 v177, v177, v120, v121
	v_max3_f32 v177, v177, v122, v123
	v_max3_f32 v177, v177, v124, v125
	v_max3_f32 v177, v177, v126, v127
	v_max3_f32 v177, v177, v128, v129
	s_waitcnt lgkmcnt(6)
	v_mfma_scale_f32_32x32x64_f8f6f4 v[50:65], v[246:253], v[90:97], v[50:65], v194, v194 op_sel_hi:[0,0,0]
	s_waitcnt lgkmcnt(4)
	v_mfma_scale_f32_32x32x64_f8f6f4 v[34:49], v[246:253], v[82:89], v[34:49], v194, v194 op_sel_hi:[0,0,0]
	s_waitcnt lgkmcnt(2)
	v_mfma_scale_f32_32x32x64_f8f6f4 v[18:33], v[246:253], v[74:81], v[18:33], v194, v194 op_sel_hi:[0,0,0]
	s_waitcnt vmcnt(0)
	s_waitcnt lgkmcnt(0)
	s_barrier
	s_waitcnt lgkmcnt(0)
	v_mfma_scale_f32_32x32x64_f8f6f4 v[2:17], v[246:253], v[66:73], v[2:17], v194, v194 op_sel_hi:[0,0,0]
	s_add_i32 m0, s98, 0x2000
	s_nop 0
	global_load_lds_dwordx4 v176, s[18:19]
	s_add_i32 m0, s98, 0x6000
	s_nop 0
	global_load_lds_dwordx4 v178, s[16:17]
	v_add_u32_e32 v176, 0x2000, v176
	v_add_u32_e32 v178, 0x20000, v178
	v_max_f32_e32 v0, v98, v99
	v_max3_f32 v0, v0, v100, v101
	v_max3_f32 v0, v0, v102, v103
	v_max3_f32 v0, v0, v104, v105
	v_max3_f32 v0, v0, v106, v107
	v_max3_f32 v0, v0, v108, v109
	v_max3_f32 v0, v0, v110, v111
	v_max3_f32 v0, v0, v112, v113
	v_max_f32_e32 v177, v177, v0
	v_mov_b32_e32 v0, v177
	v_mov_b32_e32 v221, 1.0
	s_nop 0
	v_permlane32_swap_b32_e32 v177, v0
	v_max_f32_e32 v177, v177, v0
	v_cmp_ge_f32_e32 vcc, s90, v177
	s_cmp_eq_u64 vcc, exec
	s_cbranch_scc0 .Lmla_s4_newmax
; __device__ __forceinline__ void finishSM9(f32x16& p0, f32x16& p1, float alpha, float& l_reg, v8i32& p8) {
; #pragma unroll
;   for (int r = 0; r < 16; ++r) { p0[r] = __builtin_amdgcn_exp2f(p0[r]); p1[r] = __builtin_amdgcn_exp2f(p1[r]); }
;   float ps = 0;
; #pragma unroll
;   for (int r = 0; r < 16; ++r) ps += p0[r];
; #pragma unroll
;   for (int r = 0; r < 16; ++r) ps += p1[r];
;   { auto rr = __builtin_amdgcn_permlane32_swap(__float_as_uint(ps), __float_as_uint(ps), false, false);
;     ps = __uint_as_float(rr[0]) + __uint_as_float(rr[1]); }
;   l_reg = l_reg * alpha + ps;
; #pragma unroll
;   for (int g = 0; g < 4; ++g) {
;     int w = __builtin_amdgcn_cvt_pk_fp8_f32(p0[4 * g], p0[4 * g + 1], 0, false); p8[g] = __builtin_amdgcn_cvt_pk_fp8_f32(p0[4 * g + 2], p0[4 * g + 3], w, true);
;     int u = __builtin_amdgcn_cvt_pk_fp8_f32(p1[4 * g], p1[4 * g + 1], 0, false); p8[4 + g] = __builtin_amdgcn_cvt_pk_fp8_f32(p1[4 * g + 2], p1[4 * g + 3], u, true); }
; }
; __device__ __forceinline__ void pv8(f32x16* o, const char* Vt, const v8i32 p8, int r32, int hi) {
;   const int sw = (r32 >> 2) & 3, a0 = r32 * 64 + (((hi * 2) ^ sw) << 4), a1 = r32 * 64 + (((hi * 2 + 1) ^ sw) << 4);
; #pragma unroll
;   for (int d0 = 0; d0 < 4; ++d0) {
;     const v8i32 vf = cat8(*reinterpret_cast<const v4i32*>(Vt + d0 * 2048 + a0), *reinterpret_cast<const v4i32*>(Vt + d0 * 2048 + a1));
;     o[d0] = __builtin_amdgcn_mfma_scale_f32_32x32x64_f8f6f4(p8, vf, o[d0], 0, 0, 0, 127, 0, 127); }
; }
; __device__ __forceinline__ void qkt9(f32x16& p0, f32x16& p1, const char* Kn, const char* Kr, const v8i32* qf, const float init, int r32, int hi) {
; #pragma unroll
;   for (int r = 0; r < 16; ++r) { p0[r] = init; p1[r] = init; }
; #pragma unroll
;   for (int s = 0; s < 2; ++s) { const int c0 = s * 4 + hi * 2;
;     const v8i32 a0 = cat8(*reinterpret_cast<const v4i32*>(Kn + KN8SW(r32, c0)), *reinterpret_cast<const v4i32*>(Kn + KN8SW(r32, c0 + 1)));
;     const v8i32 a1 = cat8(*reinterpret_cast<const v4i32*>(Kn + 4096 + KN8SW(r32, c0)), *reinterpret_cast<const v4i32*>(Kn + 4096 + KN8SW(r32, c0 + 1)));
;     p0 = __builtin_amdgcn_mfma_scale_f32_32x32x64_f8f6f4(a0, qf[s], p0, 0, 0, 0, 127, 0, 124);
;     p1 = __builtin_amdgcn_mfma_scale_f32_32x32x64_f8f6f4(a1, qf[s], p1, 0, 0, 0, 127, 0, 124); }
;   { const int c0 = hi * 2;
.Lmla_s4_cont:
	ds_read_b128 v[82:85], v215 offset:16384
	ds_read_b128 v[86:89], v216 offset:16384
	ds_read_b128 v[222:225], v215 offset:20480
	ds_read_b128 v[226:229], v216 offset:20480
	v_exp_f32_e32 v0, v114
	v_exp_f32_e32 v177, v115
	v_exp_f32_e32 v179, v116
	v_exp_f32_e32 v254, v117
	v_add_f32_e32 v219, v0, v177
	v_cvt_pk_fp8_f32 v246, v0, v177
	v_add_f32_e32 v219, v179, v219
	v_add_f32_e32 v219, v254, v219
	v_cvt_pk_fp8_f32 v246, v179, v254 op_sel:[0,0,1]
	s_waitcnt lgkmcnt(2)
	v_mfma_scale_f32_32x32x64_f8f6f4 v[82:97], v[82:89], v[146:153], v[230:245], v194, v193 op_sel_hi:[0,0,0]
	v_exp_f32_e32 v0, v118
	v_exp_f32_e32 v177, v119
	v_exp_f32_e32 v179, v120
	v_exp_f32_e32 v254, v121
	v_add_f32_e32 v219, v0, v219
	v_add_f32_e32 v219, v177, v219
	v_cvt_pk_fp8_f32 v247, v0, v177
	v_add_f32_e32 v219, v179, v219
	v_add_f32_e32 v219, v254, v219
	v_cvt_pk_fp8_f32 v247, v179, v254 op_sel:[0,0,1]
	ds_read_b128 v[114:117], v213 offset:16384
	ds_read_b128 v[118:121], v214 offset:16384
	s_waitcnt lgkmcnt(2)
	v_mfma_scale_f32_32x32x64_f8f6f4 v[66:81], v[222:229], v[146:153], v[230:245], v194, v193 op_sel_hi:[0,0,0]
	ds_read_b128 v[222:225], v213 offset:20480
	ds_read_b128 v[226:229], v214 offset:20480
	v_exp_f32_e32 v0, v122
	v_exp_f32_e32 v177, v123
	v_exp_f32_e32 v179, v124
	v_exp_f32_e32 v254, v125
	v_add_f32_e32 v219, v0, v219
	v_add_f32_e32 v219, v177, v219
	v_cvt_pk_fp8_f32 v248, v0, v177
	v_add_f32_e32 v219, v179, v219
	v_add_f32_e32 v219, v254, v219
	v_cvt_pk_fp8_f32 v248, v179, v254 op_sel:[0,0,1]
	v_exp_f32_e32 v0, v126
	v_exp_f32_e32 v177, v127
	v_exp_f32_e32 v179, v128
	v_exp_f32_e32 v254, v129
	v_add_f32_e32 v219, v0, v219
	v_add_f32_e32 v219, v177, v219
	v_cvt_pk_fp8_f32 v249, v0, v177
	v_add_f32_e32 v219, v179, v219
	v_add_f32_e32 v219, v254, v219
	v_cvt_pk_fp8_f32 v249, v179, v254 op_sel:[0,0,1]
	ds_read_b128 v[122:125], v185 offset:32768
	ds_read_b128 v[126:129], v186 offset:32768
	s_waitcnt lgkmcnt(4)
	v_mfma_scale_f32_32x32x64_f8f6f4 v[82:97], v[114:121], v[138:145], v[82:97], v194, v193 op_sel_hi:[0,0,0]
	v_exp_f32_e32 v0, v98
	v_exp_f32_e32 v177, v99
	v_exp_f32_e32 v179, v100
	v_exp_f32_e32 v254, v101
	v_add_f32_e32 v219, v0, v219
	v_add_f32_e32 v219, v177, v219
	v_cvt_pk_fp8_f32 v250, v0, v177
	v_add_f32_e32 v219, v179, v219
	v_add_f32_e32 v219, v254, v219
	v_cvt_pk_fp8_f32 v250, v179, v254 op_sel:[0,0,1]
	s_waitcnt lgkmcnt(2)
	v_mfma_scale_f32_32x32x64_f8f6f4 v[66:81], v[222:229], v[138:145], v[66:81], v194, v193 op_sel_hi:[0,0,0]
	ds_read_b128 v[222:225], v185 offset:34816
	ds_read_b128 v[226:229], v186 offset:34816
	v_exp_f32_e32 v0, v102
	v_exp_f32_e32 v177, v103
	v_exp_f32_e32 v179, v104
	v_exp_f32_e32 v254, v105
	v_add_f32_e32 v219, v0, v219
	v_add_f32_e32 v219, v177, v219
	v_cvt_pk_fp8_f32 v251, v0, v177
	v_add_f32_e32 v219, v179, v219
	v_add_f32_e32 v219, v254, v219
	v_cvt_pk_fp8_f32 v251, v179, v254 op_sel:[0,0,1]
	v_exp_f32_e32 v0, v106
	v_exp_f32_e32 v177, v107
	v_exp_f32_e32 v179, v108
	v_exp_f32_e32 v254, v109
	v_add_f32_e32 v219, v0, v219
	v_add_f32_e32 v219, v177, v219
	v_cvt_pk_fp8_f32 v252, v0, v177
	v_add_f32_e32 v219, v179, v219
	v_add_f32_e32 v219, v254, v219
	v_cvt_pk_fp8_f32 v252, v179, v254 op_sel:[0,0,1]
	s_waitcnt lgkmcnt(2)
	v_mfma_scale_f32_32x32x64_f8f6f4 v[82:97], v[122:129], v[130:137], v[82:97], v194, v193 op_sel_hi:[0,0,0]
	v_exp_f32_e32 v0, v110
	v_exp_f32_e32 v177, v111
	v_exp_f32_e32 v179, v112
	v_exp_f32_e32 v254, v113
	v_add_f32_e32 v219, v0, v219
	v_add_f32_e32 v219, v177, v219
	v_cvt_pk_fp8_f32 v253, v0, v177
	v_add_f32_e32 v219, v179, v219
	v_add_f32_e32 v219, v254, v219
	v_cvt_pk_fp8_f32 v253, v179, v254 op_sel:[0,0,1]
	ds_read_b128 v[122:125], v185 offset:43008
	ds_read_b128 v[126:129], v186 offset:43008
	ds_read_b128 v[114:117], v185 offset:45056
	ds_read_b128 v[118:121], v186 offset:45056
	ds_read_b128 v[106:109], v185 offset:47104
	ds_read_b128 v[110:113], v186 offset:47104
	ds_read_b128 v[98:101], v185 offset:49152
	ds_read_b128 v[102:105], v186 offset:49152
	s_waitcnt lgkmcnt(8)
	v_mfma_scale_f32_32x32x64_f8f6f4 v[66:81], v[222:229], v[130:137], v[66:81], v194, v193 op_sel_hi:[0,0,0]
	v_mov_b32_e32 v0, v219
	s_nop 1
	v_permlane32_swap_b32_e32 v219, v0
	v_add_f32_e32 v219, v219, v0
	v_fma_f32 v209, v209, v221, v219
	v_max_f32_e32 v177, v82, v83
	v_max3_f32 v177, v177, v84, v85
	v_max3_f32 v177, v177, v86, v87
	v_max3_f32 v177, v177, v88, v89
	v_max3_f32 v177, v177, v90, v91
	v_max3_f32 v177, v177, v92, v93
	v_max3_f32 v177, v177, v94, v95
	v_max3_f32 v177, v177, v96, v97
	s_waitcnt lgkmcnt(6)
	v_mfma_scale_f32_32x32x64_f8f6f4 v[50:65], v[246:253], v[122:129], v[50:65], v194, v194 op_sel_hi:[0,0,0]
	s_waitcnt lgkmcnt(4)
	v_mfma_scale_f32_32x32x64_f8f6f4 v[34:49], v[246:253], v[114:121], v[34:49], v194, v194 op_sel_hi:[0,0,0]
	s_waitcnt lgkmcnt(2)
	v_mfma_scale_f32_32x32x64_f8f6f4 v[18:33], v[246:253], v[106:113], v[18:33], v194, v194 op_sel_hi:[0,0,0]
	s_waitcnt vmcnt(0)
	s_waitcnt lgkmcnt(0)
	s_barrier
	s_waitcnt lgkmcnt(0)
	v_mfma_scale_f32_32x32x64_f8f6f4 v[2:17], v[246:253], v[98:105], v[2:17], v194, v194 op_sel_hi:[0,0,0]
	s_add_i32 m0, s98, 0xa800
	s_nop 0
	global_load_lds_dwordx4 v176, s[18:19]
	s_add_i32 m0, s98, 0xc800
	s_nop 0
	global_load_lds_dwordx4 v178, s[16:17]
	v_add_u32_e32 v176, 0x2000, v176
	v_add_u32_e32 v178, 0x20000, v178
	v_max_f32_e32 v0, v66, v67
	v_max3_f32 v0, v0, v68, v69
	v_max3_f32 v0, v0, v70, v71
	v_max3_f32 v0, v0, v72, v73
	v_max3_f32 v0, v0, v74, v75
	v_max3_f32 v0, v0, v76, v77
	v_max3_f32 v0, v0, v78, v79
	v_max3_f32 v0, v0, v80, v81
	v_max_f32_e32 v177, v177, v0
	v_mov_b32_e32 v0, v177
	v_mov_b32_e32 v218, 1.0
	s_nop 0
	v_permlane32_swap_b32_e32 v177, v0
	v_max_f32_e32 v177, v177, v0
	v_cmp_ge_f32_e32 vcc, s90, v177
	s_cmp_eq_u64 vcc, exec
	s_cbranch_scc0 .Lmla_s5_newmax
; __device__ __forceinline__ void finishSM9(f32x16& p0, f32x16& p1, float alpha, float& l_reg, v8i32& p8) {
; #pragma unroll
;   for (int r = 0; r < 16; ++r) { p0[r] = __builtin_amdgcn_exp2f(p0[r]); p1[r] = __builtin_amdgcn_exp2f(p1[r]); }
;   float ps = 0;
; #pragma unroll
;   for (int r = 0; r < 16; ++r) ps += p0[r];
; #pragma unroll
;   for (int r = 0; r < 16; ++r) ps += p1[r];
;   { auto rr = __builtin_amdgcn_permlane32_swap(__float_as_uint(ps), __float_as_uint(ps), false, false);
;     ps = __uint_as_float(rr[0]) + __uint_as_float(rr[1]); }
;   l_reg = l_reg * alpha + ps;
; #pragma unroll
;   for (int g = 0; g < 4; ++g) {
;     int w = __builtin_amdgcn_cvt_pk_fp8_f32(p0[4 * g], p0[4 * g + 1], 0, false); p8[g] = __builtin_amdgcn_cvt_pk_fp8_f32(p0[4 * g + 2], p0[4 * g + 3], w, true);
;     int u = __builtin_amdgcn_cvt_pk_fp8_f32(p1[4 * g], p1[4 * g + 1], 0, false); p8[4 + g] = __builtin_amdgcn_cvt_pk_fp8_f32(p1[4 * g + 2], p1[4 * g + 3], u, true); }
; }
; __device__ __forceinline__ void pv8(f32x16* o, const char* Vt, const v8i32 p8, int r32, int hi) {
;   const int sw = (r32 >> 2) & 3, a0 = r32 * 64 + (((hi * 2) ^ sw) << 4), a1 = r32 * 64 + (((hi * 2 + 1) ^ sw) << 4);
; #pragma unroll
;   for (int d0 = 0; d0 < 4; ++d0) {
;     const v8i32 vf = cat8(*reinterpret_cast<const v4i32*>(Vt + d0 * 2048 + a0), *reinterpret_cast<const v4i32*>(Vt + d0 * 2048 + a1));
;     o[d0] = __builtin_amdgcn_mfma_scale_f32_32x32x64_f8f6f4(p8, vf, o[d0], 0, 0, 0, 127, 0, 127); }
; }
; __device__ __forceinline__ void qkt9(f32x16& p0, f32x16& p1, const char* Kn, const char* Kr, const v8i32* qf, const float init, int r32, int hi) {
; #pragma unroll
;   for (int r = 0; r < 16; ++r) { p0[r] = init; p1[r] = init; }
; #pragma unroll
;   for (int s = 0; s < 2; ++s) { const int c0 = s * 4 + hi * 2;
;     const v8i32 a0 = cat8(*reinterpret_cast<const v4i32*>(Kn + KN8SW(r32, c0)), *reinterpret_cast<const v4i32*>(Kn + KN8SW(r32, c0 + 1)));
;     const v8i32 a1 = cat8(*reinterpret_cast<const v4i32*>(Kn + 4096 + KN8SW(r32, c0)), *reinterpret_cast<const v4i32*>(Kn + 4096 + KN8SW(r32, c0 + 1)));
;     p0 = __builtin_amdgcn_mfma_scale_f32_32x32x64_f8f6f4(a0, qf[s], p0, 0, 0, 0, 127, 0, 124);
;     p1 = __builtin_amdgcn_mfma_scale_f32_32x32x64_f8f6f4(a1, qf[s], p1, 0, 0, 0, 127, 0, 124); }
;   { const int c0 = hi * 2;
.Lmla_s5_cont:
	s_add_i32 s30, s30, 1
	s_cmpk_lt_u32 s30, 42
	s_cbranch_scc1 .Lmla_stag_loop
	ds_read_b128 v[114:117], v215 offset:24576
	ds_read_b128 v[118:121], v216 offset:24576
	ds_read_b128 v[222:225], v215 offset:28672
	ds_read_b128 v[226:229], v216 offset:28672
	v_exp_f32_e32 v0, v82
	v_exp_f32_e32 v177, v83
	v_exp_f32_e32 v179, v84
	v_exp_f32_e32 v254, v85
	v_add_f32_e32 v219, v0, v177
	v_cvt_pk_fp8_f32 v246, v0, v177
	v_add_f32_e32 v219, v179, v219
	v_add_f32_e32 v219, v254, v219
	v_cvt_pk_fp8_f32 v246, v179, v254 op_sel:[0,0,1]
	s_waitcnt lgkmcnt(2)
	v_mfma_scale_f32_32x32x64_f8f6f4 v[114:129], v[114:121], v[146:153], v[230:245], v194, v193 op_sel_hi:[0,0,0]
	v_exp_f32_e32 v0, v86
	v_exp_f32_e32 v177, v87
	v_exp_f32_e32 v179, v88
	v_exp_f32_e32 v254, v89
	v_add_f32_e32 v219, v0, v219
	v_add_f32_e32 v219, v177, v219
	v_cvt_pk_fp8_f32 v247, v0, v177
	v_add_f32_e32 v219, v179, v219
	v_add_f32_e32 v219, v254, v219
	v_cvt_pk_fp8_f32 v247, v179, v254 op_sel:[0,0,1]
	ds_read_b128 v[82:85], v213 offset:24576
	ds_read_b128 v[86:89], v214 offset:24576
	s_waitcnt lgkmcnt(2)
	v_mfma_scale_f32_32x32x64_f8f6f4 v[98:113], v[222:229], v[146:153], v[230:245], v194, v193 op_sel_hi:[0,0,0]
	ds_read_b128 v[222:225], v213 offset:28672
	ds_read_b128 v[226:229], v214 offset:28672
	v_exp_f32_e32 v0, v90
	v_exp_f32_e32 v177, v91
	v_exp_f32_e32 v179, v92
	v_exp_f32_e32 v254, v93
	v_add_f32_e32 v219, v0, v219
	v_add_f32_e32 v219, v177, v219
	v_cvt_pk_fp8_f32 v248, v0, v177
	v_add_f32_e32 v219, v179, v219
	v_add_f32_e32 v219, v254, v219
	v_cvt_pk_fp8_f32 v248, v179, v254 op_sel:[0,0,1]
	v_exp_f32_e32 v0, v94
	v_exp_f32_e32 v177, v95
	v_exp_f32_e32 v179, v96
	v_exp_f32_e32 v254, v97
	v_add_f32_e32 v219, v0, v219
	v_add_f32_e32 v219, v177, v219
	v_cvt_pk_fp8_f32 v249, v0, v177
	v_add_f32_e32 v219, v179, v219
	v_add_f32_e32 v219, v254, v219
	v_cvt_pk_fp8_f32 v249, v179, v254 op_sel:[0,0,1]
	ds_read_b128 v[90:93], v185 offset:36864
	ds_read_b128 v[94:97], v186 offset:36864
	s_waitcnt lgkmcnt(4)
	v_mfma_scale_f32_32x32x64_f8f6f4 v[114:129], v[82:89], v[138:145], v[114:129], v194, v193 op_sel_hi:[0,0,0]
	v_exp_f32_e32 v0, v66
	v_exp_f32_e32 v177, v67
	v_exp_f32_e32 v179, v68
	v_exp_f32_e32 v254, v69
	v_add_f32_e32 v219, v0, v219
	v_add_f32_e32 v219, v177, v219
	v_cvt_pk_fp8_f32 v250, v0, v177
	v_add_f32_e32 v219, v179, v219
	v_add_f32_e32 v219, v254, v219
	v_cvt_pk_fp8_f32 v250, v179, v254 op_sel:[0,0,1]
	s_waitcnt lgkmcnt(2)
	v_mfma_scale_f32_32x32x64_f8f6f4 v[98:113], v[222:229], v[138:145], v[98:113], v194, v193 op_sel_hi:[0,0,0]
	ds_read_b128 v[222:225], v185 offset:38912
	ds_read_b128 v[226:229], v186 offset:38912
	v_exp_f32_e32 v0, v70
	v_exp_f32_e32 v177, v71
	v_exp_f32_e32 v179, v72
	v_exp_f32_e32 v254, v73
	v_add_f32_e32 v219, v0, v219
	v_add_f32_e32 v219, v177, v219
	v_cvt_pk_fp8_f32 v251, v0, v177
	v_add_f32_e32 v219, v179, v219
	v_add_f32_e32 v219, v254, v219
	v_cvt_pk_fp8_f32 v251, v179, v254 op_sel:[0,0,1]
	v_exp_f32_e32 v0, v74
	v_exp_f32_e32 v177, v75
	v_exp_f32_e32 v179, v76
	v_exp_f32_e32 v254, v77
	v_add_f32_e32 v219, v0, v219
	v_add_f32_e32 v219, v177, v219
	v_cvt_pk_fp8_f32 v252, v0, v177
	v_add_f32_e32 v219, v179, v219
	v_add_f32_e32 v219, v254, v219
	v_cvt_pk_fp8_f32 v252, v179, v254 op_sel:[0,0,1]
	s_waitcnt lgkmcnt(2)
	v_mfma_scale_f32_32x32x64_f8f6f4 v[114:129], v[90:97], v[130:137], v[114:129], v194, v193 op_sel_hi:[0,0,0]
	v_exp_f32_e32 v0, v78
	v_exp_f32_e32 v177, v79
	v_exp_f32_e32 v179, v80
	v_exp_f32_e32 v254, v81
	v_add_f32_e32 v219, v0, v219
	v_add_f32_e32 v219, v177, v219
	v_cvt_pk_fp8_f32 v253, v0, v177
	v_add_f32_e32 v219, v179, v219
	v_add_f32_e32 v219, v254, v219
	v_cvt_pk_fp8_f32 v253, v179, v254 op_sel:[0,0,1]
	ds_read_b128 v[90:93], v185 offset:0
	ds_read_b128 v[94:97], v186 offset:0
	ds_read_b128 v[82:85], v185 offset:2048
	ds_read_b128 v[86:89], v186 offset:2048
	ds_read_b128 v[74:77], v185 offset:4096
	ds_read_b128 v[78:81], v186 offset:4096
	ds_read_b128 v[66:69], v185 offset:6144
	ds_read_b128 v[70:73], v186 offset:6144
	s_waitcnt lgkmcnt(8)
	v_mfma_scale_f32_32x32x64_f8f6f4 v[98:113], v[222:229], v[130:137], v[98:113], v194, v193 op_sel_hi:[0,0,0]
	v_mov_b32_e32 v0, v219
	s_nop 1
	v_permlane32_swap_b32_e32 v219, v0
	v_add_f32_e32 v219, v219, v0
	v_fma_f32 v209, v209, v218, v219
	v_max_f32_e32 v177, v114, v115
	v_max3_f32 v177, v177, v116, v117
	v_max3_f32 v177, v177, v118, v119
	v_max3_f32 v177, v177, v120, v121
	v_max3_f32 v177, v177, v122, v123
	v_max3_f32 v177, v177, v124, v125
	v_max3_f32 v177, v177, v126, v127
	v_max3_f32 v177, v177, v128, v129
	s_waitcnt lgkmcnt(6)
	v_mfma_scale_f32_32x32x64_f8f6f4 v[50:65], v[246:253], v[90:97], v[50:65], v194, v194 op_sel_hi:[0,0,0]
	s_waitcnt lgkmcnt(4)
	v_mfma_scale_f32_32x32x64_f8f6f4 v[34:49], v[246:253], v[82:89], v[34:49], v194, v194 op_sel_hi:[0,0,0]
	s_waitcnt lgkmcnt(2)
	v_mfma_scale_f32_32x32x64_f8f6f4 v[18:33], v[246:253], v[74:81], v[18:33], v194, v194 op_sel_hi:[0,0,0]
	s_waitcnt vmcnt(0)
	s_waitcnt lgkmcnt(0)
	s_barrier
	s_waitcnt lgkmcnt(0)
	v_mfma_scale_f32_32x32x64_f8f6f4 v[2:17], v[246:253], v[66:73], v[2:17], v194, v194 op_sel_hi:[0,0,0]
	s_add_i32 m0, s98, 0x0
	s_nop 0
	global_load_lds_dwordx4 v176, s[18:19]
	s_add_i32 m0, s98, 0x4000
	s_nop 0
	global_load_lds_dwordx4 v178, s[16:17]
	v_add_u32_e32 v176, 0x2000, v176
	v_add_u32_e32 v178, 0x20000, v178
	v_max_f32_e32 v0, v98, v99
	v_max3_f32 v0, v0, v100, v101
	v_max3_f32 v0, v0, v102, v103
	v_max3_f32 v0, v0, v104, v105
	v_max3_f32 v0, v0, v106, v107
	v_max3_f32 v0, v0, v108, v109
	v_max3_f32 v0, v0, v110, v111
	v_max3_f32 v0, v0, v112, v113
	v_max_f32_e32 v177, v177, v0
	v_mov_b32_e32 v0, v177
	v_mov_b32_e32 v221, 1.0
	s_nop 0
	v_permlane32_swap_b32_e32 v177, v0
	v_max_f32_e32 v177, v177, v0
	v_cmp_ge_f32_e32 vcc, s90, v177
	s_cmp_eq_u64 vcc, exec
	s_cbranch_scc0 .Lmla_q0_newmax
; __device__ __forceinline__ void finishSM9(f32x16& p0, f32x16& p1, float alpha, float& l_reg, v8i32& p8) {
; #pragma unroll
;   for (int r = 0; r < 16; ++r) { p0[r] = __builtin_amdgcn_exp2f(p0[r]); p1[r] = __builtin_amdgcn_exp2f(p1[r]); }
;   float ps = 0;
; #pragma unroll
;   for (int r = 0; r < 16; ++r) ps += p0[r];
; #pragma unroll
;   for (int r = 0; r < 16; ++r) ps += p1[r];
;   { auto rr = __builtin_amdgcn_permlane32_swap(__float_as_uint(ps), __float_as_uint(ps), false, false);
;     ps = __uint_as_float(rr[0]) + __uint_as_float(rr[1]); }
;   l_reg = l_reg * alpha + ps;
; #pragma unroll
;   for (int g = 0; g < 4; ++g) {
;     int w = __builtin_amdgcn_cvt_pk_fp8_f32(p0[4 * g], p0[4 * g + 1], 0, false); p8[g] = __builtin_amdgcn_cvt_pk_fp8_f32(p0[4 * g + 2], p0[4 * g + 3], w, true);
;     int u = __builtin_amdgcn_cvt_pk_fp8_f32(p1[4 * g], p1[4 * g + 1], 0, false); p8[4 + g] = __builtin_amdgcn_cvt_pk_fp8_f32(p1[4 * g + 2], p1[4 * g + 3], u, true); }
; }
; __device__ __forceinline__ void pv8(f32x16* o, const char* Vt, const v8i32 p8, int r32, int hi) {
;   const int sw = (r32 >> 2) & 3, a0 = r32 * 64 + (((hi * 2) ^ sw) << 4), a1 = r32 * 64 + (((hi * 2 + 1) ^ sw) << 4);
; #pragma unroll
;   for (int d0 = 0; d0 < 4; ++d0) {
;     const v8i32 vf = cat8(*reinterpret_cast<const v4i32*>(Vt + d0 * 2048 + a0), *reinterpret_cast<const v4i32*>(Vt + d0 * 2048 + a1));
;     o[d0] = __builtin_amdgcn_mfma_scale_f32_32x32x64_f8f6f4(p8, vf, o[d0], 0, 0, 0, 127, 0, 127); }
; }
; __device__ __forceinline__ void qkt9(f32x16& p0, f32x16& p1, const char* Kn, const char* Kr, const v8i32* qf, const float init, int r32, int hi) {
; #pragma unroll
;   for (int r = 0; r < 16; ++r) { p0[r] = init; p1[r] = init; }
; #pragma unroll
;   for (int s = 0; s < 2; ++s) { const int c0 = s * 4 + hi * 2;
;     const v8i32 a0 = cat8(*reinterpret_cast<const v4i32*>(Kn + KN8SW(r32, c0)), *reinterpret_cast<const v4i32*>(Kn + KN8SW(r32, c0 + 1)));
;     const v8i32 a1 = cat8(*reinterpret_cast<const v4i32*>(Kn + 4096 + KN8SW(r32, c0)), *reinterpret_cast<const v4i32*>(Kn + 4096 + KN8SW(r32, c0 + 1)));
;     p0 = __builtin_amdgcn_mfma_scale_f32_32x32x64_f8f6f4(a0, qf[s], p0, 0, 0, 0, 127, 0, 124);
;     p1 = __builtin_amdgcn_mfma_scale_f32_32x32x64_f8f6f4(a1, qf[s], p1, 0, 0, 0, 127, 0, 124); }
;   { const int c0 = hi * 2;
.Lmla_q0_cont:
	ds_read_b128 v[82:85], v215 offset:51200
	ds_read_b128 v[86:89], v216 offset:51200
	ds_read_b128 v[222:225], v215 offset:55296
	ds_read_b128 v[226:229], v216 offset:55296
	v_exp_f32_e32 v0, v114
	v_exp_f32_e32 v177, v115
	v_exp_f32_e32 v179, v116
	v_exp_f32_e32 v254, v117
	v_add_f32_e32 v219, v0, v177
	v_cvt_pk_fp8_f32 v246, v0, v177
	v_add_f32_e32 v219, v179, v219
	v_add_f32_e32 v219, v254, v219
	v_cvt_pk_fp8_f32 v246, v179, v254 op_sel:[0,0,1]
	s_waitcnt lgkmcnt(2)
	v_mfma_scale_f32_32x32x64_f8f6f4 v[82:97], v[82:89], v[146:153], v[230:245], v194, v193 op_sel_hi:[0,0,0]
	v_exp_f32_e32 v0, v118
	v_exp_f32_e32 v177, v119
	v_exp_f32_e32 v179, v120
	v_exp_f32_e32 v254, v121
	v_add_f32_e32 v219, v0, v219
	v_add_f32_e32 v219, v177, v219
	v_cvt_pk_fp8_f32 v247, v0, v177
	v_add_f32_e32 v219, v179, v219
	v_add_f32_e32 v219, v254, v219
	v_cvt_pk_fp8_f32 v247, v179, v254 op_sel:[0,0,1]
	ds_read_b128 v[114:117], v213 offset:51200
	ds_read_b128 v[118:121], v214 offset:51200
	s_waitcnt lgkmcnt(2)
	v_mfma_scale_f32_32x32x64_f8f6f4 v[66:81], v[222:229], v[146:153], v[230:245], v194, v193 op_sel_hi:[0,0,0]
	ds_read_b128 v[222:225], v213 offset:55296
	ds_read_b128 v[226:229], v214 offset:55296
	v_exp_f32_e32 v0, v122
	v_exp_f32_e32 v177, v123
	v_exp_f32_e32 v179, v124
	v_exp_f32_e32 v254, v125
	v_add_f32_e32 v219, v0, v219
	v_add_f32_e32 v219, v177, v219
	v_cvt_pk_fp8_f32 v248, v0, v177
	v_add_f32_e32 v219, v179, v219
	v_add_f32_e32 v219, v254, v219
	v_cvt_pk_fp8_f32 v248, v179, v254 op_sel:[0,0,1]
	v_exp_f32_e32 v0, v126
	v_exp_f32_e32 v177, v127
	v_exp_f32_e32 v179, v128
	v_exp_f32_e32 v254, v129
	v_add_f32_e32 v219, v0, v219
	v_add_f32_e32 v219, v177, v219
	v_cvt_pk_fp8_f32 v249, v0, v177
	v_add_f32_e32 v219, v179, v219
	v_add_f32_e32 v219, v254, v219
	v_cvt_pk_fp8_f32 v249, v179, v254 op_sel:[0,0,1]
	ds_read_b128 v[122:125], v185 offset:59392
	ds_read_b128 v[126:129], v186 offset:59392
	s_waitcnt lgkmcnt(4)
	v_mfma_scale_f32_32x32x64_f8f6f4 v[82:97], v[114:121], v[138:145], v[82:97], v194, v193 op_sel_hi:[0,0,0]
	v_exp_f32_e32 v0, v98
	v_exp_f32_e32 v177, v99
	v_exp_f32_e32 v179, v100
	v_exp_f32_e32 v254, v101
	v_add_f32_e32 v219, v0, v219
	v_add_f32_e32 v219, v177, v219
	v_cvt_pk_fp8_f32 v250, v0, v177
	v_add_f32_e32 v219, v179, v219
	v_add_f32_e32 v219, v254, v219
	v_cvt_pk_fp8_f32 v250, v179, v254 op_sel:[0,0,1]
	s_waitcnt lgkmcnt(2)
	v_mfma_scale_f32_32x32x64_f8f6f4 v[66:81], v[222:229], v[138:145], v[66:81], v194, v193 op_sel_hi:[0,0,0]
	ds_read_b128 v[222:225], v185 offset:61440
	ds_read_b128 v[226:229], v186 offset:61440
	v_exp_f32_e32 v0, v102
	v_exp_f32_e32 v177, v103
	v_exp_f32_e32 v179, v104
	v_exp_f32_e32 v254, v105
	v_add_f32_e32 v219, v0, v219
	v_add_f32_e32 v219, v177, v219
	v_cvt_pk_fp8_f32 v251, v0, v177
	v_add_f32_e32 v219, v179, v219
	v_add_f32_e32 v219, v254, v219
	v_cvt_pk_fp8_f32 v251, v179, v254 op_sel:[0,0,1]
	v_exp_f32_e32 v0, v106
	v_exp_f32_e32 v177, v107
	v_exp_f32_e32 v179, v108
	v_exp_f32_e32 v254, v109
	v_add_f32_e32 v219, v0, v219
	v_add_f32_e32 v219, v177, v219
	v_cvt_pk_fp8_f32 v252, v0, v177
	v_add_f32_e32 v219, v179, v219
	v_add_f32_e32 v219, v254, v219
	v_cvt_pk_fp8_f32 v252, v179, v254 op_sel:[0,0,1]
	s_waitcnt lgkmcnt(2)
	v_mfma_scale_f32_32x32x64_f8f6f4 v[82:97], v[122:129], v[130:137], v[82:97], v194, v193 op_sel_hi:[0,0,0]
	v_exp_f32_e32 v0, v110
	v_exp_f32_e32 v177, v111
	v_exp_f32_e32 v179, v112
	v_exp_f32_e32 v254, v113
	v_add_f32_e32 v219, v0, v219
	v_add_f32_e32 v219, v177, v219
	v_cvt_pk_fp8_f32 v253, v0, v177
	v_add_f32_e32 v219, v179, v219
	v_add_f32_e32 v219, v254, v219
	v_cvt_pk_fp8_f32 v253, v179, v254 op_sel:[0,0,1]
	ds_read_b128 v[122:125], v185 offset:8192
	ds_read_b128 v[126:129], v186 offset:8192
	ds_read_b128 v[114:117], v185 offset:10240
	ds_read_b128 v[118:121], v186 offset:10240
	ds_read_b128 v[106:109], v185 offset:12288
	ds_read_b128 v[110:113], v186 offset:12288
	ds_read_b128 v[98:101], v185 offset:14336
	ds_read_b128 v[102:105], v186 offset:14336
	s_waitcnt lgkmcnt(8)
	v_mfma_scale_f32_32x32x64_f8f6f4 v[66:81], v[222:229], v[130:137], v[66:81], v194, v193 op_sel_hi:[0,0,0]
	v_mov_b32_e32 v0, v219
	s_nop 1
	v_permlane32_swap_b32_e32 v219, v0
	v_add_f32_e32 v219, v219, v0
	v_fma_f32 v209, v209, v221, v219
	v_max_f32_e32 v177, v82, v83
	v_max3_f32 v177, v177, v84, v85
	v_max3_f32 v177, v177, v86, v87
	v_max3_f32 v177, v177, v88, v89
	v_max3_f32 v177, v177, v90, v91
	v_max3_f32 v177, v177, v92, v93
	v_max3_f32 v177, v177, v94, v95
	v_max3_f32 v177, v177, v96, v97
	s_waitcnt lgkmcnt(6)
	v_mfma_scale_f32_32x32x64_f8f6f4 v[50:65], v[246:253], v[122:129], v[50:65], v194, v194 op_sel_hi:[0,0,0]
	s_waitcnt lgkmcnt(4)
	v_mfma_scale_f32_32x32x64_f8f6f4 v[34:49], v[246:253], v[114:121], v[34:49], v194, v194 op_sel_hi:[0,0,0]
	s_waitcnt lgkmcnt(2)
	v_mfma_scale_f32_32x32x64_f8f6f4 v[18:33], v[246:253], v[106:113], v[18:33], v194, v194 op_sel_hi:[0,0,0]
	s_waitcnt vmcnt(0)
	s_waitcnt lgkmcnt(0)
	s_barrier
	s_waitcnt lgkmcnt(0)
	v_mfma_scale_f32_32x32x64_f8f6f4 v[2:17], v[246:253], v[98:105], v[2:17], v194, v194 op_sel_hi:[0,0,0]
	v_max_f32_e32 v0, v66, v67
	v_max3_f32 v0, v0, v68, v69
	v_max3_f32 v0, v0, v70, v71
	v_max3_f32 v0, v0, v72, v73
	v_max3_f32 v0, v0, v74, v75
	v_max3_f32 v0, v0, v76, v77
	v_max3_f32 v0, v0, v78, v79
	v_max3_f32 v0, v0, v80, v81
	v_max_f32_e32 v177, v177, v0
	v_mov_b32_e32 v0, v177
	v_mov_b32_e32 v218, 1.0
	s_nop 0
	v_permlane32_swap_b32_e32 v177, v0
	v_max_f32_e32 v177, v177, v0
	v_cmp_ge_f32_e32 vcc, s90, v177
	s_cmp_eq_u64 vcc, exec
	s_cbranch_scc0 .Lmla_q1_newmax
